# row scales (rsqrt of ssq) computed once per GEMM phase in the set-up and kept in spare VGPRs for P1 and P4 epilogues; no ssq loads or waits in those epilogues
# speedup vs baseline: 1.0212x; 1.0184x over previous
; __device__ __forceinline__ float ss_get(const ss_t* p) { const ss_t v = *p; return (float)(unsigned)(v >> 32) + (float)(unsigned)v * 2.3283064365386963e-10f; }
; #define PG8_WAIT_V(n) asm volatile("s_waitcnt vmcnt(" #n ")" ::: "memory")
;     __device__ __forceinline__ void operator()(const f32x4 (&acc)[2][2][4][2], const Unit& u, int wr, int wc, int fr, int fq) const {
;         int row0 = u.pm * BM + wr * 64 + fr; asm volatile("" : "+v"(row0));     const int col0 = u.pn * BM + wc * 32 + 8 * fq; const bool act = u.pn < gelu_tiles;
; #pragma unroll
;         for (int ai = 0; ai < 2; ++ai)
; #pragma unroll
;             for (int m = 0; m < 4; ++m) { const int row = row0 + ai * HALF + m * 16; bf16_t* rowp = O + (size_t)row * ldc + col0;
;                 const float rs = 1.0f / sqrtf(ss_get(ssq + row) * (1.0f / 2048.f) + 1e-6f);
; template <class Epi, class Sched, bool ALIGN_EPI = false, bool SP2 = false>
; __device__ __forceinline__ void gemm_phase(PG8_LAS unsigned char* lds, const Gemm g, const Sched& S, const Epi& E) {
;     ...
;     for (int i = 0; i < 2; ++i) { int R, C; stage_rc(tid * 16 + i * 8192, R, C); const int Rb = Epi::PERM ? ((R & ~31) + perm32(R & 31)) : R;
;         voffA[i] = (unsigned)(R * K + C) * 2u; voffB[i] = (unsigned)(Rb * K + C) * 2u; }
;     const size_t kstep = (size_t)(BK * 2);
;     const size_t hstep = (size_t)HALF * K * 2;
;     const size_t tstep = 2 * hstep;
;     const unsigned ldsw = (unsigned)wid * 1024u;
;     const int aoff = lds_byte(wr * 64 + fr, fq * 8), boff = lds_byte(wc * 32 + fr, fq * 8);
;     ...
;     Unit cur, nxt; int ui = 0;
;     if (!S.next(0, cur)) return;
;     f32x4 acc[2][2][4][2];
; #pragma unroll
;     for (int a = 0; a < 2; ++a)
; #pragma unroll
;         for (int b = 0; b < 2; ++b)
; #pragma unroll
;             for (int m = 0; m < 4; ++m)
; #pragma unroll
;                 for (int n = 0; n < 2; ++n) acc[a][b][m][n] = (f32x4){0.f, 0.f, 0.f, 0.f};
;     bf16x8 At[4][2], B0[2][2], B1[2][2];
;     const char* cA = (const char*)g.A + (size_t)cur.pm * tstep; const char* cB = (const char*)g.Bt + (size_t)cur.pn * tstep;
;     S.a_ready(cur);
;     if constexpr (SP2) {
;         PG8_STAGE(PG8_SB(0, 0), cB, voffB); PG8_STAGE(PG8_SB(0, 1), cB + hstep, voffB); PG8_STAGE(PG8_SA(0, 0), cA, voffA); PG8_STAGE(PG8_SA(0, 1), cA + hstep, voffA);
;         if (wr == 1) PG8_BAR;
;         PG8_WAIT_V(2); PG8_BAR;
.LBB0_166:
	s_andn2_b64 vcc, exec, s[2:3]
	s_cbranch_vccnz .LBB0_213
	v_readlane_b32 s2, v250, 55
	v_mov_b32_e32 v3, v204
	v_readlane_b32 s3, v250, 56
	s_andn2_b64 vcc, exec, s[2:3]
	v_readfirstlane_b32 s2, v3
	s_cbranch_vccnz .LBB0_213
	v_readlane_b32 s100, v250, 59
	v_bfe_u32 v252, v204, 8, 1
	v_and_b32_e32 v253, 15, v204
	v_lshl_or_b32 v252, v252, 6, v253
	v_add_u32_e32 v252, s100, v252
	v_mov_b32_e32 v253, 0
	v_lshl_add_u64 v[252:253], v[252:253], 3, s[4:5]
	global_load_dwordx2 v[172:173], v[252:253], off
	global_load_dwordx2 v[174:175], v[252:253], off offset:128
	global_load_dwordx2 v[176:177], v[252:253], off offset:256
	global_load_dwordx2 v[178:179], v[252:253], off offset:384
	global_load_dwordx2 v[180:181], v[252:253], off offset:1024
	global_load_dwordx2 v[182:183], v[252:253], off offset:1152
	global_load_dwordx2 v[184:185], v[252:253], off offset:1280
	global_load_dwordx2 v[186:187], v[252:253], off offset:1408
	v_lshlrev_b32_e32 v1, 4, v3
	v_add_u32_e32 v0, 0x2000, v1
	v_ashrrev_i32_e32 v4, 31, v0
	v_lshrrev_b32_e32 v4, 22, v4
	v_add_u32_e32 v4, v0, v4
	v_ashrrev_i32_e32 v8, 10, v4
	v_mul_i32_i24_e32 v4, 0x400, v8
	v_sub_u32_e32 v0, v0, v4
	v_lshrrev_b32_e32 v4, 4, v0
	v_bitop3_b32 v0, v4, v0, 32 bitop3:0x6c
	v_ashrrev_i32_e32 v4, 31, v0
	v_lshrrev_b32_e32 v4, 26, v4
	v_add_u32_e32 v4, v0, v4
	s_waitcnt lgkmcnt(0)
	v_lshlrev_b32_e32 v5, 3, v8
	v_ashrrev_i32_e32 v9, 6, v4
	v_and_b32_e32 v5, -16, v5
	v_add_u32_e32 v5, v9, v5
	v_and_b32_e32 v6, 3, v9
	s_mov_b32 s6, 0xfffe0
	v_lshrrev_b32_e32 v7, 2, v5
	v_lshlrev_b32_e32 v10, 1, v5
	v_and_b32_e32 v4, 0xc0, v4
	v_and_or_b32 v6, v5, s6, v6
	v_and_b32_e32 v7, 4, v7
	v_and_b32_e32 v10, 24, v10
	v_sub_u32_e32 v0, v0, v4
	v_or3_b32 v6, v6, v7, v10
	v_lshlrev_b32_e32 v7, 5, v8
	v_ashrrev_i16_sdwa v0, v207, sext(v0) dst_sel:DWORD dst_unused:UNUSED_PAD src0_sel:DWORD src1_sel:BYTE_0
	v_and_b32_e32 v7, 32, v7
	v_bfe_i32 v10, v0, 0, 16
	v_add_lshl_u32 v4, v7, v10, 1
	v_lshl_add_u32 v0, v6, 12, v4
	v_lshl_add_u32 v132, v5, 12, v4
	v_bfe_i32 v4, v3, 27, 1
	v_lshrrev_b32_e32 v4, 22, v4
	v_add_u32_e32 v4, v1, v4
	v_and_b32_e32 v4, 0xfffffc00, v4
	v_sub_u32_e32 v1, v1, v4
	v_lshrrev_b32_e32 v4, 4, v1
	v_ashrrev_i32_e32 v5, 31, v3
	v_bitop3_b32 v1, v4, v1, 32 bitop3:0x6c
	v_lshrrev_b32_e32 v5, 26, v5
	v_ashrrev_i32_e32 v4, 31, v1
	v_add_u32_e32 v5, v3, v5
	v_lshrrev_b32_e32 v4, 26, v4
	v_ashrrev_i32_e32 v12, 6, v5
	v_add_u32_e32 v4, v1, v4
	v_lshlrev_b32_e32 v5, 3, v12
	v_ashrrev_i32_e32 v11, 6, v4
	v_and_b32_e32 v5, -16, v5
	v_add_u32_e32 v5, v11, v5
	v_and_b32_e32 v6, 3, v11
	v_lshrrev_b32_e32 v7, 2, v5
	v_lshlrev_b32_e32 v13, 1, v5
	v_and_b32_e32 v4, 0xc0, v4
	s_ashr_i32 s10, s2, 6
	v_and_or_b32 v6, v5, s6, v6
	v_and_b32_e32 v7, 4, v7
	v_and_b32_e32 v13, 24, v13
	v_sub_u32_e32 v1, v1, v4
	s_ashr_i32 s3, s2, 8
	s_lshl_b32 s42, s10, 10
	v_or3_b32 v6, v6, v7, v13
	v_lshlrev_b32_e32 v7, 5, v12
	v_ashrrev_i16_sdwa v1, v207, sext(v1) dst_sel:DWORD dst_unused:UNUSED_PAD src0_sel:DWORD src1_sel:BYTE_0
	v_readlane_b32 s6, v247, 12
	v_and_b32_e32 v7, 32, v7
	v_bfe_i32 v13, v1, 0, 16
	v_readlane_b32 s7, v247, 13
	s_add_u32 s6, s44, s6
	v_add_lshl_u32 v1, v7, v13, 1
	s_addc_u32 s7, s45, s7
	s_add_i32 s43, s42, 0
	v_lshl_add_u32 v134, v6, 12, v1
	s_add_i32 m0, s43, 0x10000
	v_lshl_add_u32 v136, v5, 12, v1
	global_load_lds_dwordx4 v134, s[6:7]
	s_add_i32 m0, s43, 0x12000
	s_add_u32 s8, s6, 0x80000
	global_load_lds_dwordx4 v0, s[6:7]
	s_addc_u32 s9, s7, 0
	s_add_i32 m0, s43, 0x14000
	s_add_i32 s46, s43, 0x2000
	global_load_lds_dwordx4 v134, s[8:9]
	s_add_i32 m0, s43, 0x16000
	s_add_i32 s47, s43, 0x4000
	global_load_lds_dwordx4 v0, s[8:9]
	s_mov_b32 m0, s43
	v_readlane_b32 s8, v250, 57
	global_load_lds_dwordx4 v136, s[0:1]
	s_mov_b32 m0, s46
	v_readlane_b32 s9, v250, 58
	global_load_lds_dwordx4 v132, s[0:1]
	s_mov_b32 m0, s47
	s_add_i32 s48, s43, 0x6000
	v_mov_b32_e32 v135, v2
	s_nop 0
	global_load_lds_dwordx4 v136, s[8:9]
	s_mov_b32 m0, s48
	v_mov_b32_e32 v1, v2
	global_load_lds_dwordx4 v132, s[8:9]
	s_cmp_eq_u32 s3, 1
	v_lshl_add_u64 v[4:5], s[6:7], 0, v[134:135]
	s_cselect_b64 s[8:9], -1, 0
	s_cmp_lg_u32 s3, 1
	v_lshl_add_u64 v[6:7], s[6:7], 0, v[0:1]
	s_cbranch_scc1 .LBB0_170
	s_barrier
; #define PG8_STAGE(bufoff, gbase, voff) do { _Pragma("unroll") for (int _i = 0; _i < 2; ++_i) \
;         __builtin_amdgcn_global_load_lds((const unsigned*)((const char*)(gbase) + (voff)[_i]), (PG8_LAS unsigned*)(lds + (bufoff) + ldsw + _i * 8192), 16, 0, 0); } while (0)
; #define PG8_WAIT_V(n) asm volatile("s_waitcnt vmcnt(" #n ")" ::: "memory")
; #define PG8_BAR __builtin_amdgcn_s_barrier()
; __device__ __forceinline__ float ss_get(const ss_t* p) { const ss_t v = *p; return (float)(unsigned)(v >> 32) + (float)(unsigned)v * 2.3283064365386963e-10f; }
;     __device__ __forceinline__ void operator()(const f32x4 (&acc)[2][2][4][2], const Unit& u, int wr, int wc, int fr, int fq) const {
;     ...
;                 const float rs = 1.0f / sqrtf(ss_get(ssq + row) * (1.0f / 2048.f) + 1e-6f);
; template <class Epi, class Sched, bool ALIGN_EPI = false, bool SP2 = false>
; __device__ __forceinline__ void gemm_phase(PG8_LAS unsigned char* lds, const Gemm g, const Sched& S, const Epi& E) {
;     ...
;         PG8_STAGE(PG8_SB(0, 0), cB, voffB); PG8_STAGE(PG8_SB(0, 1), cB + hstep, voffB); PG8_STAGE(PG8_SA(0, 0), cA, voffA); PG8_STAGE(PG8_SA(0, 1), cA + hstep, voffA);
;         if (wr == 1) PG8_BAR;
;         PG8_WAIT_V(2); PG8_BAR;
;         PG8_STAGE(PG8_SB(1, 0), cB + kstep, voffB); PG8_STAGE(PG8_SA(1, 0), cA + kstep, voffA); PG8_STAGE(PG8_SB(1, 1), cB + hstep + kstep, voffB);
;         PG8_WAIT_V(6); PG8_BAR;
.LBB0_170:
	s_lshl_b32 s10, s10, 5
	v_mov_b32_e32 v137, v2
	s_and_b32 s13, s10, 0x60
	s_add_i32 m0, s43, 0x18000
	v_lshl_add_u64 v[4:5], v[4:5], 0, s[28:29]
	v_lshl_add_u64 v[14:15], s[0:1], 0, v[136:137]
	v_mov_b32_e32 v133, v2
	s_lshl_b32 s12, s3, 13
	s_lshl_b32 s14, s13, 7
	s_waitcnt vmcnt(2)
	s_barrier
	global_load_lds_dwordx4 v[4:5], off
	v_lshl_add_u64 v[4:5], v[6:7], 0, s[28:29]
	s_add_i32 m0, s43, 0x1a000
	s_add_i32 s49, s43, 0x8000
	s_add_i32 s50, s43, 0xa000
	v_lshl_add_u64 v[16:17], s[0:1], 0, v[132:133]
	global_load_lds_dwordx4 v[4:5], off
	v_lshl_add_u64 v[4:5], v[14:15], 0, s[28:29]
	s_mov_b32 m0, s49
	s_add_u32 s10, s6, 0x80080
	global_load_lds_dwordx4 v[4:5], off
	v_lshl_add_u64 v[4:5], v[16:17], 0, s[28:29]
	s_mov_b32 m0, s50
	s_addc_u32 s11, s7, 0
	global_load_lds_dwordx4 v[4:5], off
	s_add_i32 m0, s43, 0x1c000
	v_lshl_add_u64 v[4:5], s[10:11], 0, v[134:135]
	global_load_lds_dwordx4 v[4:5], off
	v_lshl_add_u64 v[4:5], s[10:11], 0, v[0:1]
	s_add_i32 m0, s43, 0x1e000
	v_lshrrev_b32_e32 v6, 1, v3
	global_load_lds_dwordx4 v[4:5], off
	v_and_b32_e32 v6, 24, v6
	v_and_b32_e32 v4, 15, v3
	v_lshlrev_b32_e32 v7, 1, v6
	v_lshlrev_b32_e32 v3, 2, v3
	v_lshl_or_b32 v5, s3, 6, v4
	v_lshl_or_b32 v4, v4, 6, v7
	v_and_b32_e32 v3, 32, v3
	v_bitop3_b32 v7, v4, s12, v3 bitop3:0xde
	v_bitop3_b32 v3, v4, s14, v3 bitop3:0xde
	v_lshlrev_b32_e32 v4, 15, v12
	s_cmpk_lt_u32 s2, 0x100
	v_readlane_b32 s2, v250, 59
	v_and_b32_e32 v4, 0xffff0000, v4
	v_lshl_add_u32 v4, v11, 12, v4
	v_add_u32_e32 v152, s2, v5
	v_and_b32_e32 v5, 1, v12
	v_lshl_or_b32 v4, v5, 6, v4
	v_readlane_b32 s2, v247, 10
	v_lshl_add_u32 v4, v13, 1, v4
	v_mov_b32_e32 v5, v2
	v_readlane_b32 s3, v247, 11
	s_waitcnt vmcnt(6)
	v_or_b32_e32 v153, s13, v6
	v_readlane_b32 s12, v247, 14
	v_lshl_add_u64 v[138:139], s[2:3], 0, v[4:5]
	v_lshlrev_b32_e32 v4, 15, v8
	v_and_b32_e32 v4, 0xffff0000, v4
	v_lshl_add_u32 v4, v9, 12, v4
	v_and_b32_e32 v5, 1, v8
	v_lshl_or_b32 v4, v5, 6, v4
	v_lshl_add_u32 v4, v10, 1, v4
	v_mov_b32_e32 v5, v2
	s_cselect_b64 s[10:11], -1, 0
	v_cvt_f32_u32_e32 v188, v173
	v_cvt_f32_u32_e32 v189, v172
	v_fmac_f32_e32 v188, 0x2f800000, v189
	v_fmamk_f32 v188, v188, 0x3a000000, v205
	v_rsq_f32_e32 v240, v188
	v_cvt_f32_u32_e32 v188, v175
	v_cvt_f32_u32_e32 v189, v174
	v_fmac_f32_e32 v188, 0x2f800000, v189
	v_fmamk_f32 v188, v188, 0x3a000000, v205
	v_rsq_f32_e32 v241, v188
	v_cvt_f32_u32_e32 v188, v177
	v_cvt_f32_u32_e32 v189, v176
	v_fmac_f32_e32 v188, 0x2f800000, v189
	v_fmamk_f32 v188, v188, 0x3a000000, v205
	v_rsq_f32_e32 v242, v188
	v_cvt_f32_u32_e32 v188, v179
	v_cvt_f32_u32_e32 v189, v178
	v_fmac_f32_e32 v188, 0x2f800000, v189
	v_fmamk_f32 v188, v188, 0x3a000000, v205
	v_rsq_f32_e32 v243, v188
	v_cvt_f32_u32_e32 v188, v181
	v_cvt_f32_u32_e32 v189, v180
	v_fmac_f32_e32 v188, 0x2f800000, v189
	v_fmamk_f32 v188, v188, 0x3a000000, v205
	v_rsq_f32_e32 v244, v188
	v_cvt_f32_u32_e32 v188, v183
	v_cvt_f32_u32_e32 v189, v182
	v_fmac_f32_e32 v188, 0x2f800000, v189
	v_fmamk_f32 v188, v188, 0x3a000000, v205
	v_rsq_f32_e32 v245, v188
	v_cvt_f32_u32_e32 v188, v185
	v_cvt_f32_u32_e32 v189, v184
	v_fmac_f32_e32 v188, 0x2f800000, v189
	v_fmamk_f32 v188, v188, 0x3a000000, v205
	v_rsq_f32_e32 v246, v188
	v_cvt_f32_u32_e32 v188, v187
	v_cvt_f32_u32_e32 v189, v186
	v_fmac_f32_e32 v188, 0x2f800000, v189
	v_fmamk_f32 v188, v188, 0x3a000000, v205
	v_rsq_f32_e32 v252, v188
	s_nop 0
	v_lshl_add_u64 v[140:141], s[2:3], 0, v[4:5]
	s_mov_b32 s51, 0
	v_add_u32_e32 v154, 0, v7
	v_readlane_b32 s13, v247, 15
	v_readlane_b32 s14, v248, 25
	s_barrier
	v_readlane_b32 s15, v248, 26
	s_branch .LBB0_173

; __device__ __forceinline__ float ss_get(const ss_t* p) { const ss_t v = *p; return (float)(unsigned)(v >> 32) + (float)(unsigned)v * 2.3283064365386963e-10f; }
; __device__ __forceinline__ unsigned pkbf(float lo, float hi) { typedef float f2_t __attribute__((ext_vector_type(2))); typedef __bf16 b2_t __attribute__((ext_vector_type(2))); f2_t v = {lo, hi}; b2_t b = __builtin_convertvector(v, b2_t); return __builtin_bit_cast(unsigned, b); }
; __device__ __forceinline__ f32x2 gelu_pk(f32x2 v) {
;     const f32x2 av = __builtin_elementwise_abs(v), d = av * 0.2316418882f + 1.0f;
;     f32x2 t; t.x = __builtin_amdgcn_rcpf(d.x); t.y = __builtin_amdgcn_rcpf(d.y);
;     f32x2 q = t * 0.5307027145f + (-0.7265760135f); q = q * t + 0.7107068705f; q = q * t + (-0.142248368f); q = q * t + 0.127414796f; q = q * t;
;     const f32x2 s = (v * v) * (-0.72134752044f);
;     f32x2 e; e.x = __builtin_amdgcn_exp2f(s.x); e.y = __builtin_amdgcn_exp2f(s.y);
;     const f32x2 m = v * (q * e), r = v - m;
;     f32x2 o; o.x = v.x < 0.f ? m.x : r.x; o.y = v.y < 0.f ? m.y : r.y; return o;
; }
;     __device__ __forceinline__ void operator()(const f32x4 (&acc)[2][2][4][2], const Unit& u, int wr, int wc, int fr, int fq) const {
;         int row0 = u.pm * BM + wr * 64 + fr; asm volatile("" : "+v"(row0));     const int col0 = u.pn * BM + wc * 32 + 8 * fq; const bool act = u.pn < gelu_tiles;
; #pragma unroll
;         for (int ai = 0; ai < 2; ++ai)
; #pragma unroll
;             for (int m = 0; m < 4; ++m) { const int row = row0 + ai * HALF + m * 16; bf16_t* rowp = O + (size_t)row * ldc + col0;
;                 const float rs = 1.0f / sqrtf(ss_get(ssq + row) * (1.0f / 2048.f) + 1e-6f);
; #pragma unroll
;                 for (int bj = 0; bj < 2; ++bj) { f32x4 v0 = acc[ai][bj][m][0] * rs, v1 = acc[ai][bj][m][1] * rs;
;                     if (act) { f32x2 a = gelu_pk((f32x2){v0[0], v0[1]}), b = gelu_pk((f32x2){v0[2], v0[3]}), c = gelu_pk((f32x2){v1[0], v1[1]}), d = gelu_pk((f32x2){v1[2], v1[3]});
;                         v0 = (f32x4){a.x, a.y, b.x, b.y}; v1 = (f32x4){c.x, c.y, d.x, d.y}; }
;                     u32x4 w; w.x = pkbf(v0[0], v0[1]); w.y = pkbf(v0[2], v0[3]); w.z = pkbf(v1[0], v1[1]); w.w = pkbf(v1[2], v1[3]);
;                     *(u32x4*)(rowp + bj * HALF) = w; } }
.LBB0_177:
	v_mov_b32_e32 v142, v152
	s_cmp_lt_i32 s53, 8
	v_ashrrev_i32_e32 v143, 31, v142
	v_lshl_add_u64 v[144:145], v[142:143], 3, s[4:5]
	s_flbit_i32_b32 s2, 0
	v_mov_b32_e32 v149, v2
	s_cselect_b64 s[40:41], -1, 0
	s_min_u32 s15, s2, 32
	s_sub_i32 s52, 32, s15
	s_cmp_gt_i32 s53, 7
	v_mov_b32_e32 v146, v240
	s_nop 1
	s_nop 0
	s_nop 1
	s_nop 1
	s_nop 1
	v_pk_mul_f32 v[130:131], v[130:131], v[146:147] op_sel_hi:[1,0]
	v_pk_mul_f32 v[128:129], v[128:129], v[146:147] op_sel_hi:[1,0]
	v_pk_mul_f32 v[148:149], v[126:127], v[146:147] op_sel_hi:[1,0]
	v_pk_mul_f32 v[150:151], v[124:125], v[146:147] op_sel_hi:[1,0]
	s_cbranch_scc1 .LBB0_179
	v_and_b32_e32 v125, 0x7fffffff, v129
	v_and_b32_e32 v124, 0x7fffffff, v128
	v_pk_fma_f32 v[124:125], v[124:125], s[90:91], 1.0 op_sel_hi:[1,0,0]
	s_mov_b32 s2, 0xbf3a00e3
	v_rcp_f32_e32 v126, v124
	v_rcp_f32_e32 v127, v125
	v_mov_b64_e32 v[124:125], s[2:3]
	v_pk_mul_f32 v[158:159], v[128:129], v[128:129]
	s_mov_b32 s2, 0xbf38aa3b
	v_pk_fma_f32 v[156:157], v[126:127], s[92:93], v[124:125] op_sel_hi:[1,0,0]
	v_pk_mul_f32 v[158:159], v[158:159], s[2:3] op_sel_hi:[1,0]
	v_pk_fma_f32 v[156:157], v[126:127], v[156:157], s[94:95] op_sel_hi:[1,1,0]
	v_exp_f32_e32 v158, v158
	v_exp_f32_e32 v159, v159
	v_pk_fma_f32 v[156:157], v[126:127], v[156:157], s[96:97] op_sel_hi:[1,1,0]
	v_cmp_gt_f32_e32 vcc, 0, v128
	v_pk_fma_f32 v[156:157], v[126:127], v[156:157], s[30:31] op_sel_hi:[1,1,0]
	s_nop 0
	v_pk_mul_f32 v[126:127], v[126:127], v[156:157]
	v_pk_mul_f32 v[156:157], v[130:131], v[130:131]
	v_pk_mul_f32 v[126:127], v[158:159], v[126:127]
	v_pk_mul_f32 v[156:157], v[156:157], s[2:3] op_sel_hi:[1,0]
	v_pk_mul_f32 v[158:159], v[128:129], v[126:127]
	v_pk_fma_f32 v[126:127], v[128:129], v[126:127], v[128:129] neg_lo:[1,0,0] neg_hi:[1,0,0]
	v_exp_f32_e32 v156, v156
	v_cndmask_b32_e32 v128, v126, v158, vcc
	v_cmp_gt_f32_e32 vcc, 0, v129
	v_and_b32_e32 v126, 0x7fffffff, v130
	v_exp_f32_e32 v157, v157
	v_cndmask_b32_e32 v129, v127, v159, vcc
	v_and_b32_e32 v127, 0x7fffffff, v131
	v_pk_fma_f32 v[126:127], v[126:127], s[90:91], 1.0 op_sel_hi:[1,0,0]
	v_cmp_gt_f32_e32 vcc, 0, v130
	v_rcp_f32_e32 v126, v126
	v_rcp_f32_e32 v127, v127
	s_nop 0
	v_pk_fma_f32 v[158:159], v[126:127], s[92:93], v[124:125] op_sel_hi:[1,0,0]
	s_nop 0
	v_pk_fma_f32 v[158:159], v[126:127], v[158:159], s[94:95] op_sel_hi:[1,1,0]
	s_nop 0
	v_pk_fma_f32 v[158:159], v[126:127], v[158:159], s[96:97] op_sel_hi:[1,1,0]
	s_nop 0
	v_pk_fma_f32 v[158:159], v[126:127], v[158:159], s[30:31] op_sel_hi:[1,1,0]
	s_nop 0
	v_pk_mul_f32 v[126:127], v[126:127], v[158:159]
	v_pk_mul_f32 v[158:159], v[150:151], v[150:151]
	v_pk_mul_f32 v[126:127], v[156:157], v[126:127]
	v_pk_mul_f32 v[158:159], v[158:159], s[2:3] op_sel_hi:[1,0]
	v_pk_mul_f32 v[156:157], v[130:131], v[126:127]
	v_pk_fma_f32 v[126:127], v[130:131], v[126:127], v[130:131] neg_lo:[1,0,0] neg_hi:[1,0,0]
	v_exp_f32_e32 v158, v158
	v_cndmask_b32_e32 v130, v126, v156, vcc
	v_cmp_gt_f32_e32 vcc, 0, v131
	v_and_b32_e32 v126, 0x7fffffff, v150
	v_exp_f32_e32 v159, v159
	v_cndmask_b32_e32 v131, v127, v157, vcc
	v_and_b32_e32 v127, 0x7fffffff, v151
	v_pk_fma_f32 v[126:127], v[126:127], s[90:91], 1.0 op_sel_hi:[1,0,0]
	v_cmp_gt_f32_e32 vcc, 0, v150
	v_rcp_f32_e32 v126, v126
	v_rcp_f32_e32 v127, v127
	s_nop 0
	v_pk_fma_f32 v[156:157], v[126:127], s[92:93], v[124:125] op_sel_hi:[1,0,0]
	s_nop 0
	v_pk_fma_f32 v[156:157], v[126:127], v[156:157], s[94:95] op_sel_hi:[1,1,0]
	s_nop 0
	v_pk_fma_f32 v[156:157], v[126:127], v[156:157], s[96:97] op_sel_hi:[1,1,0]
	s_nop 0
	v_pk_fma_f32 v[156:157], v[126:127], v[156:157], s[30:31] op_sel_hi:[1,1,0]
	s_nop 0
	v_pk_mul_f32 v[126:127], v[126:127], v[156:157]
	v_pk_mul_f32 v[156:157], v[148:149], v[148:149]
	v_pk_mul_f32 v[126:127], v[158:159], v[126:127]
	s_nop 0
	v_pk_mul_f32 v[158:159], v[150:151], v[126:127]
	v_pk_fma_f32 v[126:127], v[150:151], v[126:127], v[150:151] neg_lo:[1,0,0] neg_hi:[1,0,0]
	s_nop 0
	v_cndmask_b32_e32 v150, v126, v158, vcc
	v_cmp_gt_f32_e32 vcc, 0, v151
	v_and_b32_e32 v126, 0x7fffffff, v148
	s_nop 0
	v_cndmask_b32_e32 v151, v127, v159, vcc
	v_and_b32_e32 v127, 0x7fffffff, v149
	v_pk_fma_f32 v[126:127], v[126:127], s[90:91], 1.0 op_sel_hi:[1,0,0]
	v_cmp_gt_f32_e32 vcc, 0, v148
	v_rcp_f32_e32 v126, v126
	v_rcp_f32_e32 v127, v127
	s_nop 0
	v_pk_fma_f32 v[124:125], v[126:127], s[92:93], v[124:125] op_sel_hi:[1,0,0]
	s_nop 0
	v_pk_fma_f32 v[124:125], v[126:127], v[124:125], s[94:95] op_sel_hi:[1,1,0]
	s_nop 0
	v_pk_fma_f32 v[124:125], v[126:127], v[124:125], s[96:97] op_sel_hi:[1,1,0]
	s_nop 0
	v_pk_fma_f32 v[124:125], v[126:127], v[124:125], s[30:31] op_sel_hi:[1,1,0]
	s_nop 0
	v_pk_mul_f32 v[124:125], v[126:127], v[124:125]
	v_pk_mul_f32 v[126:127], v[156:157], s[2:3] op_sel_hi:[1,0]
	s_nop 0
	v_exp_f32_e32 v126, v126
	v_exp_f32_e32 v127, v127
	s_nop 0
	v_pk_mul_f32 v[124:125], v[126:127], v[124:125]
	s_nop 0
	v_pk_mul_f32 v[126:127], v[148:149], v[124:125]
	v_pk_fma_f32 v[124:125], v[148:149], v[124:125], v[148:149] neg_lo:[1,0,0] neg_hi:[1,0,0]
	s_nop 0
	v_cndmask_b32_e32 v148, v124, v126, vcc
	v_cmp_gt_f32_e32 vcc, 0, v149
	s_nop 1
	v_cndmask_b32_e32 v149, v125, v127, vcc

; __device__ __forceinline__ unsigned pkbf(float lo, float hi) { typedef float f2_t __attribute__((ext_vector_type(2))); typedef __bf16 b2_t __attribute__((ext_vector_type(2))); f2_t v = {lo, hi}; b2_t b = __builtin_convertvector(v, b2_t); return __builtin_bit_cast(unsigned, b); }
; __device__ __forceinline__ f32x2 gelu_pk(f32x2 v) {
;     const f32x2 av = __builtin_elementwise_abs(v), d = av * 0.2316418882f + 1.0f;
;     f32x2 t; t.x = __builtin_amdgcn_rcpf(d.x); t.y = __builtin_amdgcn_rcpf(d.y);
;     f32x2 q = t * 0.5307027145f + (-0.7265760135f); q = q * t + 0.7107068705f; q = q * t + (-0.142248368f); q = q * t + 0.127414796f; q = q * t;
;     const f32x2 s = (v * v) * (-0.72134752044f);
;     f32x2 e; e.x = __builtin_amdgcn_exp2f(s.x); e.y = __builtin_amdgcn_exp2f(s.y);
;     const f32x2 m = v * (q * e), r = v - m;
;     f32x2 o; o.x = v.x < 0.f ? m.x : r.x; o.y = v.y < 0.f ? m.y : r.y; return o;
; }
;     __device__ __forceinline__ void operator()(const f32x4 (&acc)[2][2][4][2], const Unit& u, int wr, int wc, int fr, int fq) const {
;     ...
;                 for (int bj = 0; bj < 2; ++bj) { f32x4 v0 = acc[ai][bj][m][0] * rs, v1 = acc[ai][bj][m][1] * rs;
;                     if (act) { f32x2 a = gelu_pk((f32x2){v0[0], v0[1]}), b = gelu_pk((f32x2){v0[2], v0[3]}), c = gelu_pk((f32x2){v1[0], v1[1]}), d = gelu_pk((f32x2){v1[2], v1[3]});
;                         v0 = (f32x4){a.x, a.y, b.x, b.y}; v1 = (f32x4){c.x, c.y, d.x, d.y}; }
;                     u32x4 w; w.x = pkbf(v0[0], v0[1]); w.y = pkbf(v0[2], v0[3]); w.z = pkbf(v1[0], v1[1]); w.w = pkbf(v1[2], v1[3]);
;                     *(u32x4*)(rowp + bj * HALF) = w; } }
.LBB0_181:
	v_cvt_pk_bf16_f32 v120, v120, v121
	v_cvt_pk_bf16_f32 v121, v122, v123
	v_cvt_pk_bf16_f32 v122, v116, v117
	v_cvt_pk_bf16_f32 v123, v118, v119
	global_store_dwordx4 v[126:127], v[120:123], off offset:256
	s_nop 0
	v_mov_b32_e32 v119, v2
	v_mov_b32_e32 v116, v241
	s_nop 1
	s_nop 0
	s_nop 1
	s_nop 1
	s_nop 1
	s_and_b64 vcc, exec, s[36:37]
	v_pk_mul_f32 v[114:115], v[114:115], v[116:117] op_sel_hi:[1,0]
	v_pk_mul_f32 v[118:119], v[112:113], v[116:117] op_sel_hi:[1,0]
	v_pk_mul_f32 v[110:111], v[110:111], v[116:117] op_sel_hi:[1,0]
	v_pk_mul_f32 v[112:113], v[108:109], v[116:117] op_sel_hi:[1,0]
	s_cbranch_vccnz .LBB0_183
	v_and_b32_e32 v109, 0x7fffffff, v119
	v_and_b32_e32 v108, 0x7fffffff, v118
	v_pk_fma_f32 v[108:109], v[108:109], s[90:91], 1.0 op_sel_hi:[1,0,0]
	s_mov_b32 s2, 0xbf3a00e3
	v_rcp_f32_e32 v120, v108
	v_rcp_f32_e32 v121, v109
	v_mov_b64_e32 v[108:109], s[2:3]
	v_pk_mul_f32 v[126:127], v[118:119], v[118:119]
	s_mov_b32 s2, 0xbf38aa3b
	v_pk_fma_f32 v[122:123], v[120:121], s[92:93], v[108:109] op_sel_hi:[1,0,0]
	v_pk_mul_f32 v[126:127], v[126:127], s[2:3] op_sel_hi:[1,0]
	v_pk_fma_f32 v[122:123], v[120:121], v[122:123], s[94:95] op_sel_hi:[1,1,0]
	v_exp_f32_e32 v126, v126
	v_exp_f32_e32 v127, v127
	v_pk_fma_f32 v[122:123], v[120:121], v[122:123], s[96:97] op_sel_hi:[1,1,0]
	v_cmp_gt_f32_e32 vcc, 0, v118
	v_pk_fma_f32 v[122:123], v[120:121], v[122:123], s[30:31] op_sel_hi:[1,1,0]
	s_nop 0
	v_pk_mul_f32 v[120:121], v[120:121], v[122:123]
	v_pk_mul_f32 v[122:123], v[114:115], v[114:115]
	v_pk_mul_f32 v[120:121], v[126:127], v[120:121]
	v_pk_mul_f32 v[122:123], v[122:123], s[2:3] op_sel_hi:[1,0]
	v_pk_mul_f32 v[126:127], v[118:119], v[120:121]
	v_pk_fma_f32 v[120:121], v[118:119], v[120:121], v[118:119] neg_lo:[1,0,0] neg_hi:[1,0,0]
	v_exp_f32_e32 v122, v122
	v_cndmask_b32_e32 v118, v120, v126, vcc
	v_cmp_gt_f32_e32 vcc, 0, v119
	v_and_b32_e32 v120, 0x7fffffff, v114
	v_exp_f32_e32 v123, v123
	v_cndmask_b32_e32 v119, v121, v127, vcc
	v_and_b32_e32 v121, 0x7fffffff, v115
	v_pk_fma_f32 v[120:121], v[120:121], s[90:91], 1.0 op_sel_hi:[1,0,0]
	v_cmp_gt_f32_e32 vcc, 0, v114
	v_rcp_f32_e32 v120, v120
	v_rcp_f32_e32 v121, v121
	s_nop 0
	v_pk_fma_f32 v[126:127], v[120:121], s[92:93], v[108:109] op_sel_hi:[1,0,0]
	s_nop 0
	v_pk_fma_f32 v[126:127], v[120:121], v[126:127], s[94:95] op_sel_hi:[1,1,0]
	s_nop 0
	v_pk_fma_f32 v[126:127], v[120:121], v[126:127], s[96:97] op_sel_hi:[1,1,0]
	s_nop 0
	v_pk_fma_f32 v[126:127], v[120:121], v[126:127], s[30:31] op_sel_hi:[1,1,0]
	s_nop 0
	v_pk_mul_f32 v[120:121], v[120:121], v[126:127]
	v_pk_mul_f32 v[126:127], v[112:113], v[112:113]
	v_pk_mul_f32 v[120:121], v[122:123], v[120:121]
	v_pk_mul_f32 v[126:127], v[126:127], s[2:3] op_sel_hi:[1,0]
	v_pk_mul_f32 v[122:123], v[114:115], v[120:121]
	v_pk_fma_f32 v[120:121], v[114:115], v[120:121], v[114:115] neg_lo:[1,0,0] neg_hi:[1,0,0]
	v_exp_f32_e32 v126, v126
	v_cndmask_b32_e32 v114, v120, v122, vcc
	v_cmp_gt_f32_e32 vcc, 0, v115
	v_and_b32_e32 v120, 0x7fffffff, v112
	v_exp_f32_e32 v127, v127
	v_cndmask_b32_e32 v115, v121, v123, vcc
	v_and_b32_e32 v121, 0x7fffffff, v113
	v_pk_fma_f32 v[120:121], v[120:121], s[90:91], 1.0 op_sel_hi:[1,0,0]
	v_cmp_gt_f32_e32 vcc, 0, v112
	v_rcp_f32_e32 v120, v120
	v_rcp_f32_e32 v121, v121
	s_nop 0
	v_pk_fma_f32 v[122:123], v[120:121], s[92:93], v[108:109] op_sel_hi:[1,0,0]
	s_nop 0
	v_pk_fma_f32 v[122:123], v[120:121], v[122:123], s[94:95] op_sel_hi:[1,1,0]
	s_nop 0
	v_pk_fma_f32 v[122:123], v[120:121], v[122:123], s[96:97] op_sel_hi:[1,1,0]
	s_nop 0
	v_pk_fma_f32 v[122:123], v[120:121], v[122:123], s[30:31] op_sel_hi:[1,1,0]
	s_nop 0
	v_pk_mul_f32 v[120:121], v[120:121], v[122:123]
	v_pk_mul_f32 v[122:123], v[110:111], v[110:111]
	v_pk_mul_f32 v[120:121], v[126:127], v[120:121]
	s_nop 0
	v_pk_mul_f32 v[126:127], v[112:113], v[120:121]
	v_pk_fma_f32 v[120:121], v[112:113], v[120:121], v[112:113] neg_lo:[1,0,0] neg_hi:[1,0,0]
	s_nop 0
	v_cndmask_b32_e32 v112, v120, v126, vcc
	v_cmp_gt_f32_e32 vcc, 0, v113
	v_and_b32_e32 v120, 0x7fffffff, v110
	s_nop 0
	v_cndmask_b32_e32 v113, v121, v127, vcc
	v_and_b32_e32 v121, 0x7fffffff, v111
	v_pk_fma_f32 v[120:121], v[120:121], s[90:91], 1.0 op_sel_hi:[1,0,0]
	v_cmp_gt_f32_e32 vcc, 0, v110
	v_rcp_f32_e32 v120, v120
	v_rcp_f32_e32 v121, v121
	s_nop 0
	v_pk_fma_f32 v[108:109], v[120:121], s[92:93], v[108:109] op_sel_hi:[1,0,0]
	s_nop 0
	v_pk_fma_f32 v[108:109], v[120:121], v[108:109], s[94:95] op_sel_hi:[1,1,0]
	s_nop 0
	v_pk_fma_f32 v[108:109], v[120:121], v[108:109], s[96:97] op_sel_hi:[1,1,0]
	s_nop 0
	v_pk_fma_f32 v[108:109], v[120:121], v[108:109], s[30:31] op_sel_hi:[1,1,0]
	s_nop 0
	v_pk_mul_f32 v[108:109], v[120:121], v[108:109]
	v_pk_mul_f32 v[120:121], v[122:123], s[2:3] op_sel_hi:[1,0]
	s_nop 0
	v_exp_f32_e32 v120, v120
	v_exp_f32_e32 v121, v121
	s_nop 0
	v_pk_mul_f32 v[108:109], v[120:121], v[108:109]
	s_nop 0
	v_pk_mul_f32 v[120:121], v[110:111], v[108:109]
	v_pk_fma_f32 v[108:109], v[110:111], v[108:109], v[110:111] neg_lo:[1,0,0] neg_hi:[1,0,0]
	s_nop 0
	v_cndmask_b32_e32 v110, v108, v120, vcc
	v_cmp_gt_f32_e32 vcc, 0, v111
	s_nop 1
	v_cndmask_b32_e32 v111, v109, v121, vcc

; __device__ __forceinline__ float ss_get(const ss_t* p) { const ss_t v = *p; return (float)(unsigned)(v >> 32) + (float)(unsigned)v * 2.3283064365386963e-10f; }
; __device__ __forceinline__ unsigned pkbf(float lo, float hi) { typedef float f2_t __attribute__((ext_vector_type(2))); typedef __bf16 b2_t __attribute__((ext_vector_type(2))); f2_t v = {lo, hi}; b2_t b = __builtin_convertvector(v, b2_t); return __builtin_bit_cast(unsigned, b); }
; __device__ __forceinline__ f32x2 gelu_pk(f32x2 v) {
;     const f32x2 av = __builtin_elementwise_abs(v), d = av * 0.2316418882f + 1.0f;
;     f32x2 t; t.x = __builtin_amdgcn_rcpf(d.x); t.y = __builtin_amdgcn_rcpf(d.y);
;     f32x2 q = t * 0.5307027145f + (-0.7265760135f); q = q * t + 0.7107068705f; q = q * t + (-0.142248368f); q = q * t + 0.127414796f; q = q * t;
;     const f32x2 s = (v * v) * (-0.72134752044f);
;     f32x2 e; e.x = __builtin_amdgcn_exp2f(s.x); e.y = __builtin_amdgcn_exp2f(s.y);
;     const f32x2 m = v * (q * e), r = v - m;
;     f32x2 o; o.x = v.x < 0.f ? m.x : r.x; o.y = v.y < 0.f ? m.y : r.y; return o;
; }
;     __device__ __forceinline__ void operator()(const f32x4 (&acc)[2][2][4][2], const Unit& u, int wr, int wc, int fr, int fq) const {
;     ...
;             for (int m = 0; m < 4; ++m) { const int row = row0 + ai * HALF + m * 16; bf16_t* rowp = O + (size_t)row * ldc + col0;
;                 const float rs = 1.0f / sqrtf(ss_get(ssq + row) * (1.0f / 2048.f) + 1e-6f);
; #pragma unroll
;                 for (int bj = 0; bj < 2; ++bj) { f32x4 v0 = acc[ai][bj][m][0] * rs, v1 = acc[ai][bj][m][1] * rs;
;                     if (act) { f32x2 a = gelu_pk((f32x2){v0[0], v0[1]}), b = gelu_pk((f32x2){v0[2], v0[3]}), c = gelu_pk((f32x2){v1[0], v1[1]}), d = gelu_pk((f32x2){v1[2], v1[3]});
;                         v0 = (f32x4){a.x, a.y, b.x, b.y}; v1 = (f32x4){c.x, c.y, d.x, d.y}; }
;                     u32x4 w; w.x = pkbf(v0[0], v0[1]); w.y = pkbf(v0[2], v0[3]); w.z = pkbf(v1[0], v1[1]); w.w = pkbf(v1[2], v1[3]);
;                     *(u32x4*)(rowp + bj * HALF) = w; } }
.LBB0_185:
	v_cvt_pk_bf16_f32 v104, v104, v105
	v_cvt_pk_bf16_f32 v105, v106, v107
	v_cvt_pk_bf16_f32 v106, v100, v101
	v_cvt_pk_bf16_f32 v107, v102, v103
	global_store_dwordx4 v[108:109], v[104:107], off offset:256
	s_nop 0
	v_mov_b32_e32 v103, v2
	v_mov_b32_e32 v100, v242
	s_nop 1
	s_nop 0
	s_nop 1
	s_nop 1
	s_nop 1
	s_and_b64 vcc, exec, s[36:37]
	v_pk_mul_f32 v[98:99], v[98:99], v[100:101] op_sel_hi:[1,0]
	v_pk_mul_f32 v[102:103], v[96:97], v[100:101] op_sel_hi:[1,0]
	v_pk_mul_f32 v[94:95], v[94:95], v[100:101] op_sel_hi:[1,0]
	v_pk_mul_f32 v[96:97], v[92:93], v[100:101] op_sel_hi:[1,0]
	s_cbranch_vccnz .LBB0_187
	v_and_b32_e32 v93, 0x7fffffff, v103
	v_and_b32_e32 v92, 0x7fffffff, v102
	v_pk_fma_f32 v[92:93], v[92:93], s[90:91], 1.0 op_sel_hi:[1,0,0]
	s_mov_b32 s2, 0xbf3a00e3
	v_rcp_f32_e32 v104, v92
	v_rcp_f32_e32 v105, v93
	v_mov_b64_e32 v[92:93], s[2:3]
	v_pk_mul_f32 v[108:109], v[102:103], v[102:103]
	s_mov_b32 s2, 0xbf38aa3b
	v_pk_fma_f32 v[106:107], v[104:105], s[92:93], v[92:93] op_sel_hi:[1,0,0]
	v_pk_mul_f32 v[108:109], v[108:109], s[2:3] op_sel_hi:[1,0]
	v_pk_fma_f32 v[106:107], v[104:105], v[106:107], s[94:95] op_sel_hi:[1,1,0]
	v_exp_f32_e32 v108, v108
	v_exp_f32_e32 v109, v109
	v_pk_fma_f32 v[106:107], v[104:105], v[106:107], s[96:97] op_sel_hi:[1,1,0]
	v_cmp_gt_f32_e32 vcc, 0, v102
	v_pk_fma_f32 v[106:107], v[104:105], v[106:107], s[30:31] op_sel_hi:[1,1,0]
	s_nop 0
	v_pk_mul_f32 v[104:105], v[104:105], v[106:107]
	v_pk_mul_f32 v[106:107], v[98:99], v[98:99]
	v_pk_mul_f32 v[104:105], v[108:109], v[104:105]
	v_pk_mul_f32 v[106:107], v[106:107], s[2:3] op_sel_hi:[1,0]
	v_pk_mul_f32 v[108:109], v[102:103], v[104:105]
	v_pk_fma_f32 v[104:105], v[102:103], v[104:105], v[102:103] neg_lo:[1,0,0] neg_hi:[1,0,0]
	v_exp_f32_e32 v106, v106
	v_cndmask_b32_e32 v102, v104, v108, vcc
	v_cmp_gt_f32_e32 vcc, 0, v103
	v_and_b32_e32 v104, 0x7fffffff, v98
	v_exp_f32_e32 v107, v107
	v_cndmask_b32_e32 v103, v105, v109, vcc
	v_and_b32_e32 v105, 0x7fffffff, v99
	v_pk_fma_f32 v[104:105], v[104:105], s[90:91], 1.0 op_sel_hi:[1,0,0]
	v_cmp_gt_f32_e32 vcc, 0, v98
	v_rcp_f32_e32 v104, v104
	v_rcp_f32_e32 v105, v105
	s_nop 0
	v_pk_fma_f32 v[108:109], v[104:105], s[92:93], v[92:93] op_sel_hi:[1,0,0]
	s_nop 0
	v_pk_fma_f32 v[108:109], v[104:105], v[108:109], s[94:95] op_sel_hi:[1,1,0]
	s_nop 0
	v_pk_fma_f32 v[108:109], v[104:105], v[108:109], s[96:97] op_sel_hi:[1,1,0]
	s_nop 0
	v_pk_fma_f32 v[108:109], v[104:105], v[108:109], s[30:31] op_sel_hi:[1,1,0]
	s_nop 0
	v_pk_mul_f32 v[104:105], v[104:105], v[108:109]
	v_pk_mul_f32 v[108:109], v[96:97], v[96:97]
	v_pk_mul_f32 v[104:105], v[106:107], v[104:105]
	v_pk_mul_f32 v[108:109], v[108:109], s[2:3] op_sel_hi:[1,0]
	v_pk_mul_f32 v[106:107], v[98:99], v[104:105]
	v_pk_fma_f32 v[104:105], v[98:99], v[104:105], v[98:99] neg_lo:[1,0,0] neg_hi:[1,0,0]
	v_exp_f32_e32 v108, v108
	v_cndmask_b32_e32 v98, v104, v106, vcc
	v_cmp_gt_f32_e32 vcc, 0, v99
	v_and_b32_e32 v104, 0x7fffffff, v96
	v_exp_f32_e32 v109, v109
	v_cndmask_b32_e32 v99, v105, v107, vcc
	v_and_b32_e32 v105, 0x7fffffff, v97
	v_pk_fma_f32 v[104:105], v[104:105], s[90:91], 1.0 op_sel_hi:[1,0,0]
	v_cmp_gt_f32_e32 vcc, 0, v96
	v_rcp_f32_e32 v104, v104
	v_rcp_f32_e32 v105, v105
	s_nop 0
	v_pk_fma_f32 v[106:107], v[104:105], s[92:93], v[92:93] op_sel_hi:[1,0,0]
	s_nop 0
	v_pk_fma_f32 v[106:107], v[104:105], v[106:107], s[94:95] op_sel_hi:[1,1,0]
	s_nop 0
	v_pk_fma_f32 v[106:107], v[104:105], v[106:107], s[96:97] op_sel_hi:[1,1,0]
	s_nop 0
	v_pk_fma_f32 v[106:107], v[104:105], v[106:107], s[30:31] op_sel_hi:[1,1,0]
	s_nop 0
	v_pk_mul_f32 v[104:105], v[104:105], v[106:107]
	v_pk_mul_f32 v[106:107], v[94:95], v[94:95]
	v_pk_mul_f32 v[104:105], v[108:109], v[104:105]
	s_nop 0
	v_pk_mul_f32 v[108:109], v[96:97], v[104:105]
	v_pk_fma_f32 v[104:105], v[96:97], v[104:105], v[96:97] neg_lo:[1,0,0] neg_hi:[1,0,0]
	s_nop 0
	v_cndmask_b32_e32 v96, v104, v108, vcc
	v_cmp_gt_f32_e32 vcc, 0, v97
	v_and_b32_e32 v104, 0x7fffffff, v94
	s_nop 0
	v_cndmask_b32_e32 v97, v105, v109, vcc
	v_and_b32_e32 v105, 0x7fffffff, v95
	v_pk_fma_f32 v[104:105], v[104:105], s[90:91], 1.0 op_sel_hi:[1,0,0]
	v_cmp_gt_f32_e32 vcc, 0, v94
	v_rcp_f32_e32 v104, v104
	v_rcp_f32_e32 v105, v105
	s_nop 0
	v_pk_fma_f32 v[92:93], v[104:105], s[92:93], v[92:93] op_sel_hi:[1,0,0]
	s_nop 0
	v_pk_fma_f32 v[92:93], v[104:105], v[92:93], s[94:95] op_sel_hi:[1,1,0]
	s_nop 0
	v_pk_fma_f32 v[92:93], v[104:105], v[92:93], s[96:97] op_sel_hi:[1,1,0]
	s_nop 0
	v_pk_fma_f32 v[92:93], v[104:105], v[92:93], s[30:31] op_sel_hi:[1,1,0]
	s_nop 0
	v_pk_mul_f32 v[92:93], v[104:105], v[92:93]
	v_pk_mul_f32 v[104:105], v[106:107], s[2:3] op_sel_hi:[1,0]
	s_nop 0
	v_exp_f32_e32 v104, v104
	v_exp_f32_e32 v105, v105
	s_nop 0
	v_pk_mul_f32 v[92:93], v[104:105], v[92:93]
	s_nop 0
	v_pk_mul_f32 v[104:105], v[94:95], v[92:93]
	v_pk_fma_f32 v[92:93], v[94:95], v[92:93], v[94:95] neg_lo:[1,0,0] neg_hi:[1,0,0]
	s_nop 0
	v_cndmask_b32_e32 v94, v92, v104, vcc
	v_cmp_gt_f32_e32 vcc, 0, v95
	s_nop 1
	v_cndmask_b32_e32 v95, v93, v105, vcc

; __device__ __forceinline__ float ss_get(const ss_t* p) { const ss_t v = *p; return (float)(unsigned)(v >> 32) + (float)(unsigned)v * 2.3283064365386963e-10f; }
; __device__ __forceinline__ unsigned pkbf(float lo, float hi) { typedef float f2_t __attribute__((ext_vector_type(2))); typedef __bf16 b2_t __attribute__((ext_vector_type(2))); f2_t v = {lo, hi}; b2_t b = __builtin_convertvector(v, b2_t); return __builtin_bit_cast(unsigned, b); }
; __device__ __forceinline__ f32x2 gelu_pk(f32x2 v) {
;     const f32x2 av = __builtin_elementwise_abs(v), d = av * 0.2316418882f + 1.0f;
;     f32x2 t; t.x = __builtin_amdgcn_rcpf(d.x); t.y = __builtin_amdgcn_rcpf(d.y);
;     f32x2 q = t * 0.5307027145f + (-0.7265760135f); q = q * t + 0.7107068705f; q = q * t + (-0.142248368f); q = q * t + 0.127414796f; q = q * t;
;     const f32x2 s = (v * v) * (-0.72134752044f);
;     f32x2 e; e.x = __builtin_amdgcn_exp2f(s.x); e.y = __builtin_amdgcn_exp2f(s.y);
;     const f32x2 m = v * (q * e), r = v - m;
;     f32x2 o; o.x = v.x < 0.f ? m.x : r.x; o.y = v.y < 0.f ? m.y : r.y; return o;
; }
;     __device__ __forceinline__ void operator()(const f32x4 (&acc)[2][2][4][2], const Unit& u, int wr, int wc, int fr, int fq) const {
;     ...
;             for (int m = 0; m < 4; ++m) { const int row = row0 + ai * HALF + m * 16; bf16_t* rowp = O + (size_t)row * ldc + col0;
;                 const float rs = 1.0f / sqrtf(ss_get(ssq + row) * (1.0f / 2048.f) + 1e-6f);
; #pragma unroll
;                 for (int bj = 0; bj < 2; ++bj) { f32x4 v0 = acc[ai][bj][m][0] * rs, v1 = acc[ai][bj][m][1] * rs;
;                     if (act) { f32x2 a = gelu_pk((f32x2){v0[0], v0[1]}), b = gelu_pk((f32x2){v0[2], v0[3]}), c = gelu_pk((f32x2){v1[0], v1[1]}), d = gelu_pk((f32x2){v1[2], v1[3]});
;                         v0 = (f32x4){a.x, a.y, b.x, b.y}; v1 = (f32x4){c.x, c.y, d.x, d.y}; }
;                     u32x4 w; w.x = pkbf(v0[0], v0[1]); w.y = pkbf(v0[2], v0[3]); w.z = pkbf(v1[0], v1[1]); w.w = pkbf(v1[2], v1[3]);
;                     *(u32x4*)(rowp + bj * HALF) = w; } }
.LBB0_189:
	v_cvt_pk_bf16_f32 v88, v88, v89
	v_cvt_pk_bf16_f32 v89, v90, v91
	v_cvt_pk_bf16_f32 v90, v84, v85
	v_cvt_pk_bf16_f32 v91, v86, v87
	global_store_dwordx4 v[92:93], v[88:91], off offset:256
	s_nop 0
	v_mov_b32_e32 v87, v2
	v_mov_b32_e32 v84, v243
	s_nop 1
	s_nop 0
	s_nop 1
	s_nop 1
	s_nop 1
	s_and_b64 vcc, exec, s[36:37]
	v_pk_mul_f32 v[82:83], v[82:83], v[84:85] op_sel_hi:[1,0]
	v_pk_mul_f32 v[86:87], v[80:81], v[84:85] op_sel_hi:[1,0]
	v_pk_mul_f32 v[78:79], v[78:79], v[84:85] op_sel_hi:[1,0]
	v_pk_mul_f32 v[80:81], v[76:77], v[84:85] op_sel_hi:[1,0]
	s_cbranch_vccnz .LBB0_191
	v_and_b32_e32 v77, 0x7fffffff, v87
	v_and_b32_e32 v76, 0x7fffffff, v86
	v_pk_fma_f32 v[76:77], v[76:77], s[90:91], 1.0 op_sel_hi:[1,0,0]
	s_mov_b32 s2, 0xbf3a00e3
	v_rcp_f32_e32 v88, v76
	v_rcp_f32_e32 v89, v77
	v_mov_b64_e32 v[76:77], s[2:3]
	v_pk_mul_f32 v[92:93], v[86:87], v[86:87]
	s_mov_b32 s2, 0xbf38aa3b
	v_pk_fma_f32 v[90:91], v[88:89], s[92:93], v[76:77] op_sel_hi:[1,0,0]
	v_pk_mul_f32 v[92:93], v[92:93], s[2:3] op_sel_hi:[1,0]
	v_pk_fma_f32 v[90:91], v[88:89], v[90:91], s[94:95] op_sel_hi:[1,1,0]
	v_exp_f32_e32 v92, v92
	v_exp_f32_e32 v93, v93
	v_pk_fma_f32 v[90:91], v[88:89], v[90:91], s[96:97] op_sel_hi:[1,1,0]
	v_cmp_gt_f32_e32 vcc, 0, v86
	v_pk_fma_f32 v[90:91], v[88:89], v[90:91], s[30:31] op_sel_hi:[1,1,0]
	s_nop 0
	v_pk_mul_f32 v[88:89], v[88:89], v[90:91]
	v_pk_mul_f32 v[90:91], v[82:83], v[82:83]
	v_pk_mul_f32 v[88:89], v[92:93], v[88:89]
	v_pk_mul_f32 v[90:91], v[90:91], s[2:3] op_sel_hi:[1,0]
	v_pk_mul_f32 v[92:93], v[86:87], v[88:89]
	v_pk_fma_f32 v[88:89], v[86:87], v[88:89], v[86:87] neg_lo:[1,0,0] neg_hi:[1,0,0]
	v_exp_f32_e32 v90, v90
	v_cndmask_b32_e32 v86, v88, v92, vcc
	v_cmp_gt_f32_e32 vcc, 0, v87
	v_and_b32_e32 v88, 0x7fffffff, v82
	v_exp_f32_e32 v91, v91
	v_cndmask_b32_e32 v87, v89, v93, vcc
	v_and_b32_e32 v89, 0x7fffffff, v83
	v_pk_fma_f32 v[88:89], v[88:89], s[90:91], 1.0 op_sel_hi:[1,0,0]
	v_cmp_gt_f32_e32 vcc, 0, v82
	v_rcp_f32_e32 v88, v88
	v_rcp_f32_e32 v89, v89
	s_nop 0
	v_pk_fma_f32 v[92:93], v[88:89], s[92:93], v[76:77] op_sel_hi:[1,0,0]
	s_nop 0
	v_pk_fma_f32 v[92:93], v[88:89], v[92:93], s[94:95] op_sel_hi:[1,1,0]
	s_nop 0
	v_pk_fma_f32 v[92:93], v[88:89], v[92:93], s[96:97] op_sel_hi:[1,1,0]
	s_nop 0
	v_pk_fma_f32 v[92:93], v[88:89], v[92:93], s[30:31] op_sel_hi:[1,1,0]
	s_nop 0
	v_pk_mul_f32 v[88:89], v[88:89], v[92:93]
	v_pk_mul_f32 v[92:93], v[80:81], v[80:81]
	v_pk_mul_f32 v[88:89], v[90:91], v[88:89]
	v_pk_mul_f32 v[92:93], v[92:93], s[2:3] op_sel_hi:[1,0]
	v_pk_mul_f32 v[90:91], v[82:83], v[88:89]
	v_pk_fma_f32 v[88:89], v[82:83], v[88:89], v[82:83] neg_lo:[1,0,0] neg_hi:[1,0,0]
	v_exp_f32_e32 v92, v92
	v_cndmask_b32_e32 v82, v88, v90, vcc
	v_cmp_gt_f32_e32 vcc, 0, v83
	v_and_b32_e32 v88, 0x7fffffff, v80
	v_exp_f32_e32 v93, v93
	v_cndmask_b32_e32 v83, v89, v91, vcc
	v_and_b32_e32 v89, 0x7fffffff, v81
	v_pk_fma_f32 v[88:89], v[88:89], s[90:91], 1.0 op_sel_hi:[1,0,0]
	v_cmp_gt_f32_e32 vcc, 0, v80
	v_rcp_f32_e32 v88, v88
	v_rcp_f32_e32 v89, v89
	s_nop 0
	v_pk_fma_f32 v[90:91], v[88:89], s[92:93], v[76:77] op_sel_hi:[1,0,0]
	s_nop 0
	v_pk_fma_f32 v[90:91], v[88:89], v[90:91], s[94:95] op_sel_hi:[1,1,0]
	s_nop 0
	v_pk_fma_f32 v[90:91], v[88:89], v[90:91], s[96:97] op_sel_hi:[1,1,0]
	s_nop 0
	v_pk_fma_f32 v[90:91], v[88:89], v[90:91], s[30:31] op_sel_hi:[1,1,0]
	s_nop 0
	v_pk_mul_f32 v[88:89], v[88:89], v[90:91]
	v_pk_mul_f32 v[90:91], v[78:79], v[78:79]
	v_pk_mul_f32 v[88:89], v[92:93], v[88:89]
	s_nop 0
	v_pk_mul_f32 v[92:93], v[80:81], v[88:89]
	v_pk_fma_f32 v[88:89], v[80:81], v[88:89], v[80:81] neg_lo:[1,0,0] neg_hi:[1,0,0]
	s_nop 0
	v_cndmask_b32_e32 v80, v88, v92, vcc
	v_cmp_gt_f32_e32 vcc, 0, v81
	v_and_b32_e32 v88, 0x7fffffff, v78
	s_nop 0
	v_cndmask_b32_e32 v81, v89, v93, vcc
	v_and_b32_e32 v89, 0x7fffffff, v79
	v_pk_fma_f32 v[88:89], v[88:89], s[90:91], 1.0 op_sel_hi:[1,0,0]
	v_cmp_gt_f32_e32 vcc, 0, v78
	v_rcp_f32_e32 v88, v88
	v_rcp_f32_e32 v89, v89
	s_nop 0
	v_pk_fma_f32 v[76:77], v[88:89], s[92:93], v[76:77] op_sel_hi:[1,0,0]
	s_nop 0
	v_pk_fma_f32 v[76:77], v[88:89], v[76:77], s[94:95] op_sel_hi:[1,1,0]
	s_nop 0
	v_pk_fma_f32 v[76:77], v[88:89], v[76:77], s[96:97] op_sel_hi:[1,1,0]
	s_nop 0
	v_pk_fma_f32 v[76:77], v[88:89], v[76:77], s[30:31] op_sel_hi:[1,1,0]
	s_nop 0
	v_pk_mul_f32 v[76:77], v[88:89], v[76:77]
	v_pk_mul_f32 v[88:89], v[90:91], s[2:3] op_sel_hi:[1,0]
	s_nop 0
	v_exp_f32_e32 v88, v88
	v_exp_f32_e32 v89, v89
	s_nop 0
	v_pk_mul_f32 v[76:77], v[88:89], v[76:77]
	s_nop 0
	v_pk_mul_f32 v[88:89], v[78:79], v[76:77]
	v_pk_fma_f32 v[76:77], v[78:79], v[76:77], v[78:79] neg_lo:[1,0,0] neg_hi:[1,0,0]
	s_nop 0
	v_cndmask_b32_e32 v78, v76, v88, vcc
	v_cmp_gt_f32_e32 vcc, 0, v79
	s_nop 1
	v_cndmask_b32_e32 v79, v77, v89, vcc

; __device__ __forceinline__ float ss_get(const ss_t* p) { const ss_t v = *p; return (float)(unsigned)(v >> 32) + (float)(unsigned)v * 2.3283064365386963e-10f; }
; __device__ __forceinline__ unsigned pkbf(float lo, float hi) { typedef float f2_t __attribute__((ext_vector_type(2))); typedef __bf16 b2_t __attribute__((ext_vector_type(2))); f2_t v = {lo, hi}; b2_t b = __builtin_convertvector(v, b2_t); return __builtin_bit_cast(unsigned, b); }
; __device__ __forceinline__ f32x2 gelu_pk(f32x2 v) {
;     const f32x2 av = __builtin_elementwise_abs(v), d = av * 0.2316418882f + 1.0f;
;     f32x2 t; t.x = __builtin_amdgcn_rcpf(d.x); t.y = __builtin_amdgcn_rcpf(d.y);
;     f32x2 q = t * 0.5307027145f + (-0.7265760135f); q = q * t + 0.7107068705f; q = q * t + (-0.142248368f); q = q * t + 0.127414796f; q = q * t;
;     const f32x2 s = (v * v) * (-0.72134752044f);
;     f32x2 e; e.x = __builtin_amdgcn_exp2f(s.x); e.y = __builtin_amdgcn_exp2f(s.y);
;     const f32x2 m = v * (q * e), r = v - m;
;     f32x2 o; o.x = v.x < 0.f ? m.x : r.x; o.y = v.y < 0.f ? m.y : r.y; return o;
; }
;     __device__ __forceinline__ void operator()(const f32x4 (&acc)[2][2][4][2], const Unit& u, int wr, int wc, int fr, int fq) const {
;     ...
;             for (int m = 0; m < 4; ++m) { const int row = row0 + ai * HALF + m * 16; bf16_t* rowp = O + (size_t)row * ldc + col0;
;                 const float rs = 1.0f / sqrtf(ss_get(ssq + row) * (1.0f / 2048.f) + 1e-6f);
; #pragma unroll
;                 for (int bj = 0; bj < 2; ++bj) { f32x4 v0 = acc[ai][bj][m][0] * rs, v1 = acc[ai][bj][m][1] * rs;
;                     if (act) { f32x2 a = gelu_pk((f32x2){v0[0], v0[1]}), b = gelu_pk((f32x2){v0[2], v0[3]}), c = gelu_pk((f32x2){v1[0], v1[1]}), d = gelu_pk((f32x2){v1[2], v1[3]});
;                         v0 = (f32x4){a.x, a.y, b.x, b.y}; v1 = (f32x4){c.x, c.y, d.x, d.y}; }
;                     u32x4 w; w.x = pkbf(v0[0], v0[1]); w.y = pkbf(v0[2], v0[3]); w.z = pkbf(v1[0], v1[1]); w.w = pkbf(v1[2], v1[3]);
;                     *(u32x4*)(rowp + bj * HALF) = w; } }
.LBB0_193:
	v_cvt_pk_bf16_f32 v72, v72, v73
	v_cvt_pk_bf16_f32 v73, v74, v75
	v_cvt_pk_bf16_f32 v74, v68, v69
	v_cvt_pk_bf16_f32 v75, v70, v71
	global_store_dwordx4 v[76:77], v[72:75], off offset:256
	s_nop 0
	v_mov_b32_e32 v71, v2
	v_mov_b32_e32 v68, v244
	s_nop 1
	s_nop 0
	s_nop 1
	s_nop 1
	s_nop 1
	s_and_b64 vcc, exec, s[36:37]
	v_pk_mul_f32 v[66:67], v[66:67], v[68:69] op_sel_hi:[1,0]
	v_pk_mul_f32 v[70:71], v[64:65], v[68:69] op_sel_hi:[1,0]
	v_pk_mul_f32 v[62:63], v[62:63], v[68:69] op_sel_hi:[1,0]
	v_pk_mul_f32 v[64:65], v[60:61], v[68:69] op_sel_hi:[1,0]
	s_cbranch_vccnz .LBB0_195
	v_and_b32_e32 v61, 0x7fffffff, v71
	v_and_b32_e32 v60, 0x7fffffff, v70
	v_pk_fma_f32 v[60:61], v[60:61], s[90:91], 1.0 op_sel_hi:[1,0,0]
	s_mov_b32 s2, 0xbf3a00e3
	v_rcp_f32_e32 v72, v60
	v_rcp_f32_e32 v73, v61
	v_mov_b64_e32 v[60:61], s[2:3]
	v_pk_mul_f32 v[76:77], v[70:71], v[70:71]
	s_mov_b32 s2, 0xbf38aa3b
	v_pk_fma_f32 v[74:75], v[72:73], s[92:93], v[60:61] op_sel_hi:[1,0,0]
	v_pk_mul_f32 v[76:77], v[76:77], s[2:3] op_sel_hi:[1,0]
	v_pk_fma_f32 v[74:75], v[72:73], v[74:75], s[94:95] op_sel_hi:[1,1,0]
	v_exp_f32_e32 v76, v76
	v_exp_f32_e32 v77, v77
	v_pk_fma_f32 v[74:75], v[72:73], v[74:75], s[96:97] op_sel_hi:[1,1,0]
	v_cmp_gt_f32_e32 vcc, 0, v70
	v_pk_fma_f32 v[74:75], v[72:73], v[74:75], s[30:31] op_sel_hi:[1,1,0]
	s_nop 0
	v_pk_mul_f32 v[72:73], v[72:73], v[74:75]
	v_pk_mul_f32 v[74:75], v[66:67], v[66:67]
	v_pk_mul_f32 v[72:73], v[76:77], v[72:73]
	v_pk_mul_f32 v[74:75], v[74:75], s[2:3] op_sel_hi:[1,0]
	v_pk_mul_f32 v[76:77], v[70:71], v[72:73]
	v_pk_fma_f32 v[72:73], v[70:71], v[72:73], v[70:71] neg_lo:[1,0,0] neg_hi:[1,0,0]
	v_exp_f32_e32 v74, v74
	v_cndmask_b32_e32 v70, v72, v76, vcc
	v_cmp_gt_f32_e32 vcc, 0, v71
	v_and_b32_e32 v72, 0x7fffffff, v66
	v_exp_f32_e32 v75, v75
	v_cndmask_b32_e32 v71, v73, v77, vcc
	v_and_b32_e32 v73, 0x7fffffff, v67
	v_pk_fma_f32 v[72:73], v[72:73], s[90:91], 1.0 op_sel_hi:[1,0,0]
	v_cmp_gt_f32_e32 vcc, 0, v66
	v_rcp_f32_e32 v72, v72
	v_rcp_f32_e32 v73, v73
	s_nop 0
	v_pk_fma_f32 v[76:77], v[72:73], s[92:93], v[60:61] op_sel_hi:[1,0,0]
	s_nop 0
	v_pk_fma_f32 v[76:77], v[72:73], v[76:77], s[94:95] op_sel_hi:[1,1,0]
	s_nop 0
	v_pk_fma_f32 v[76:77], v[72:73], v[76:77], s[96:97] op_sel_hi:[1,1,0]
	s_nop 0
	v_pk_fma_f32 v[76:77], v[72:73], v[76:77], s[30:31] op_sel_hi:[1,1,0]
	s_nop 0
	v_pk_mul_f32 v[72:73], v[72:73], v[76:77]
	v_pk_mul_f32 v[76:77], v[64:65], v[64:65]
	v_pk_mul_f32 v[72:73], v[74:75], v[72:73]
	v_pk_mul_f32 v[76:77], v[76:77], s[2:3] op_sel_hi:[1,0]
	v_pk_mul_f32 v[74:75], v[66:67], v[72:73]
	v_pk_fma_f32 v[72:73], v[66:67], v[72:73], v[66:67] neg_lo:[1,0,0] neg_hi:[1,0,0]
	v_exp_f32_e32 v76, v76
	v_cndmask_b32_e32 v66, v72, v74, vcc
	v_cmp_gt_f32_e32 vcc, 0, v67
	v_and_b32_e32 v72, 0x7fffffff, v64
	v_exp_f32_e32 v77, v77
	v_cndmask_b32_e32 v67, v73, v75, vcc
	v_and_b32_e32 v73, 0x7fffffff, v65
	v_pk_fma_f32 v[72:73], v[72:73], s[90:91], 1.0 op_sel_hi:[1,0,0]
	v_cmp_gt_f32_e32 vcc, 0, v64
	v_rcp_f32_e32 v72, v72
	v_rcp_f32_e32 v73, v73
	s_nop 0
	v_pk_fma_f32 v[74:75], v[72:73], s[92:93], v[60:61] op_sel_hi:[1,0,0]
	s_nop 0
	v_pk_fma_f32 v[74:75], v[72:73], v[74:75], s[94:95] op_sel_hi:[1,1,0]
	s_nop 0
	v_pk_fma_f32 v[74:75], v[72:73], v[74:75], s[96:97] op_sel_hi:[1,1,0]
	s_nop 0
	v_pk_fma_f32 v[74:75], v[72:73], v[74:75], s[30:31] op_sel_hi:[1,1,0]
	s_nop 0
	v_pk_mul_f32 v[72:73], v[72:73], v[74:75]
	v_pk_mul_f32 v[74:75], v[62:63], v[62:63]
	v_pk_mul_f32 v[72:73], v[76:77], v[72:73]
	s_nop 0
	v_pk_mul_f32 v[76:77], v[64:65], v[72:73]
	v_pk_fma_f32 v[72:73], v[64:65], v[72:73], v[64:65] neg_lo:[1,0,0] neg_hi:[1,0,0]
	s_nop 0
	v_cndmask_b32_e32 v64, v72, v76, vcc
	v_cmp_gt_f32_e32 vcc, 0, v65
	v_and_b32_e32 v72, 0x7fffffff, v62
	s_nop 0
	v_cndmask_b32_e32 v65, v73, v77, vcc
	v_and_b32_e32 v73, 0x7fffffff, v63
	v_pk_fma_f32 v[72:73], v[72:73], s[90:91], 1.0 op_sel_hi:[1,0,0]
	v_cmp_gt_f32_e32 vcc, 0, v62
	v_rcp_f32_e32 v72, v72
	v_rcp_f32_e32 v73, v73
	s_nop 0
	v_pk_fma_f32 v[60:61], v[72:73], s[92:93], v[60:61] op_sel_hi:[1,0,0]
	s_nop 0
	v_pk_fma_f32 v[60:61], v[72:73], v[60:61], s[94:95] op_sel_hi:[1,1,0]
	s_nop 0
	v_pk_fma_f32 v[60:61], v[72:73], v[60:61], s[96:97] op_sel_hi:[1,1,0]
	s_nop 0
	v_pk_fma_f32 v[60:61], v[72:73], v[60:61], s[30:31] op_sel_hi:[1,1,0]
	s_nop 0
	v_pk_mul_f32 v[60:61], v[72:73], v[60:61]
	v_pk_mul_f32 v[72:73], v[74:75], s[2:3] op_sel_hi:[1,0]
	s_nop 0
	v_exp_f32_e32 v72, v72
	v_exp_f32_e32 v73, v73
	s_nop 0
	v_pk_mul_f32 v[60:61], v[72:73], v[60:61]
	s_nop 0
	v_pk_mul_f32 v[72:73], v[62:63], v[60:61]
	v_pk_fma_f32 v[60:61], v[62:63], v[60:61], v[62:63] neg_lo:[1,0,0] neg_hi:[1,0,0]
	s_nop 0
	v_cndmask_b32_e32 v62, v60, v72, vcc
	v_cmp_gt_f32_e32 vcc, 0, v63
	s_nop 1
	v_cndmask_b32_e32 v63, v61, v73, vcc

; __device__ __forceinline__ float ss_get(const ss_t* p) { const ss_t v = *p; return (float)(unsigned)(v >> 32) + (float)(unsigned)v * 2.3283064365386963e-10f; }
; __device__ __forceinline__ unsigned pkbf(float lo, float hi) { typedef float f2_t __attribute__((ext_vector_type(2))); typedef __bf16 b2_t __attribute__((ext_vector_type(2))); f2_t v = {lo, hi}; b2_t b = __builtin_convertvector(v, b2_t); return __builtin_bit_cast(unsigned, b); }
; __device__ __forceinline__ f32x2 gelu_pk(f32x2 v) {
;     const f32x2 av = __builtin_elementwise_abs(v), d = av * 0.2316418882f + 1.0f;
;     f32x2 t; t.x = __builtin_amdgcn_rcpf(d.x); t.y = __builtin_amdgcn_rcpf(d.y);
;     f32x2 q = t * 0.5307027145f + (-0.7265760135f); q = q * t + 0.7107068705f; q = q * t + (-0.142248368f); q = q * t + 0.127414796f; q = q * t;
;     const f32x2 s = (v * v) * (-0.72134752044f);
;     f32x2 e; e.x = __builtin_amdgcn_exp2f(s.x); e.y = __builtin_amdgcn_exp2f(s.y);
;     const f32x2 m = v * (q * e), r = v - m;
;     f32x2 o; o.x = v.x < 0.f ? m.x : r.x; o.y = v.y < 0.f ? m.y : r.y; return o;
; }
;     __device__ __forceinline__ void operator()(const f32x4 (&acc)[2][2][4][2], const Unit& u, int wr, int wc, int fr, int fq) const {
;     ...
;             for (int m = 0; m < 4; ++m) { const int row = row0 + ai * HALF + m * 16; bf16_t* rowp = O + (size_t)row * ldc + col0;
;                 const float rs = 1.0f / sqrtf(ss_get(ssq + row) * (1.0f / 2048.f) + 1e-6f);
; #pragma unroll
;                 for (int bj = 0; bj < 2; ++bj) { f32x4 v0 = acc[ai][bj][m][0] * rs, v1 = acc[ai][bj][m][1] * rs;
;                     if (act) { f32x2 a = gelu_pk((f32x2){v0[0], v0[1]}), b = gelu_pk((f32x2){v0[2], v0[3]}), c = gelu_pk((f32x2){v1[0], v1[1]}), d = gelu_pk((f32x2){v1[2], v1[3]});
;                         v0 = (f32x4){a.x, a.y, b.x, b.y}; v1 = (f32x4){c.x, c.y, d.x, d.y}; }
;                     u32x4 w; w.x = pkbf(v0[0], v0[1]); w.y = pkbf(v0[2], v0[3]); w.z = pkbf(v1[0], v1[1]); w.w = pkbf(v1[2], v1[3]);
;                     *(u32x4*)(rowp + bj * HALF) = w; } }
.LBB0_197:
	v_cvt_pk_bf16_f32 v56, v56, v57
	v_cvt_pk_bf16_f32 v57, v58, v59
	v_cvt_pk_bf16_f32 v58, v52, v53
	v_cvt_pk_bf16_f32 v59, v54, v55
	global_store_dwordx4 v[60:61], v[56:59], off offset:256
	s_nop 0
	v_mov_b32_e32 v55, v2
	v_mov_b32_e32 v52, v245
	s_nop 1
	s_nop 0
	s_nop 1
	s_nop 1
	s_nop 1
	s_and_b64 vcc, exec, s[36:37]
	v_pk_mul_f32 v[50:51], v[50:51], v[52:53] op_sel_hi:[1,0]
	v_pk_mul_f32 v[54:55], v[48:49], v[52:53] op_sel_hi:[1,0]
	v_pk_mul_f32 v[46:47], v[46:47], v[52:53] op_sel_hi:[1,0]
	v_pk_mul_f32 v[48:49], v[44:45], v[52:53] op_sel_hi:[1,0]
	s_cbranch_vccnz .LBB0_199
	v_and_b32_e32 v45, 0x7fffffff, v55
	v_and_b32_e32 v44, 0x7fffffff, v54
	v_pk_fma_f32 v[44:45], v[44:45], s[90:91], 1.0 op_sel_hi:[1,0,0]
	s_mov_b32 s2, 0xbf3a00e3
	v_rcp_f32_e32 v56, v44
	v_rcp_f32_e32 v57, v45
	v_mov_b64_e32 v[44:45], s[2:3]
	v_pk_mul_f32 v[60:61], v[54:55], v[54:55]
	s_mov_b32 s2, 0xbf38aa3b
	v_pk_fma_f32 v[58:59], v[56:57], s[92:93], v[44:45] op_sel_hi:[1,0,0]
	v_pk_mul_f32 v[60:61], v[60:61], s[2:3] op_sel_hi:[1,0]
	v_pk_fma_f32 v[58:59], v[56:57], v[58:59], s[94:95] op_sel_hi:[1,1,0]
	v_exp_f32_e32 v60, v60
	v_exp_f32_e32 v61, v61
	v_pk_fma_f32 v[58:59], v[56:57], v[58:59], s[96:97] op_sel_hi:[1,1,0]
	v_cmp_gt_f32_e32 vcc, 0, v54
	v_pk_fma_f32 v[58:59], v[56:57], v[58:59], s[30:31] op_sel_hi:[1,1,0]
	s_nop 0
	v_pk_mul_f32 v[56:57], v[56:57], v[58:59]
	v_pk_mul_f32 v[58:59], v[50:51], v[50:51]
	v_pk_mul_f32 v[56:57], v[60:61], v[56:57]
	v_pk_mul_f32 v[58:59], v[58:59], s[2:3] op_sel_hi:[1,0]
	v_pk_mul_f32 v[60:61], v[54:55], v[56:57]
	v_pk_fma_f32 v[56:57], v[54:55], v[56:57], v[54:55] neg_lo:[1,0,0] neg_hi:[1,0,0]
	v_exp_f32_e32 v58, v58
	v_cndmask_b32_e32 v54, v56, v60, vcc
	v_cmp_gt_f32_e32 vcc, 0, v55
	v_and_b32_e32 v56, 0x7fffffff, v50
	v_exp_f32_e32 v59, v59
	v_cndmask_b32_e32 v55, v57, v61, vcc
	v_and_b32_e32 v57, 0x7fffffff, v51
	v_pk_fma_f32 v[56:57], v[56:57], s[90:91], 1.0 op_sel_hi:[1,0,0]
	v_cmp_gt_f32_e32 vcc, 0, v50
	v_rcp_f32_e32 v56, v56
	v_rcp_f32_e32 v57, v57
	s_nop 0
	v_pk_fma_f32 v[60:61], v[56:57], s[92:93], v[44:45] op_sel_hi:[1,0,0]
	s_nop 0
	v_pk_fma_f32 v[60:61], v[56:57], v[60:61], s[94:95] op_sel_hi:[1,1,0]
	s_nop 0
	v_pk_fma_f32 v[60:61], v[56:57], v[60:61], s[96:97] op_sel_hi:[1,1,0]
	s_nop 0
	v_pk_fma_f32 v[60:61], v[56:57], v[60:61], s[30:31] op_sel_hi:[1,1,0]
	s_nop 0
	v_pk_mul_f32 v[56:57], v[56:57], v[60:61]
	v_pk_mul_f32 v[60:61], v[48:49], v[48:49]
	v_pk_mul_f32 v[56:57], v[58:59], v[56:57]
	v_pk_mul_f32 v[60:61], v[60:61], s[2:3] op_sel_hi:[1,0]
	v_pk_mul_f32 v[58:59], v[50:51], v[56:57]
	v_pk_fma_f32 v[56:57], v[50:51], v[56:57], v[50:51] neg_lo:[1,0,0] neg_hi:[1,0,0]
	v_exp_f32_e32 v60, v60
	v_cndmask_b32_e32 v50, v56, v58, vcc
	v_cmp_gt_f32_e32 vcc, 0, v51
	v_and_b32_e32 v56, 0x7fffffff, v48
	v_exp_f32_e32 v61, v61
	v_cndmask_b32_e32 v51, v57, v59, vcc
	v_and_b32_e32 v57, 0x7fffffff, v49
	v_pk_fma_f32 v[56:57], v[56:57], s[90:91], 1.0 op_sel_hi:[1,0,0]
	v_cmp_gt_f32_e32 vcc, 0, v48
	v_rcp_f32_e32 v56, v56
	v_rcp_f32_e32 v57, v57
	s_nop 0
	v_pk_fma_f32 v[58:59], v[56:57], s[92:93], v[44:45] op_sel_hi:[1,0,0]
	s_nop 0
	v_pk_fma_f32 v[58:59], v[56:57], v[58:59], s[94:95] op_sel_hi:[1,1,0]
	s_nop 0
	v_pk_fma_f32 v[58:59], v[56:57], v[58:59], s[96:97] op_sel_hi:[1,1,0]
	s_nop 0
	v_pk_fma_f32 v[58:59], v[56:57], v[58:59], s[30:31] op_sel_hi:[1,1,0]
	s_nop 0
	v_pk_mul_f32 v[56:57], v[56:57], v[58:59]
	v_pk_mul_f32 v[58:59], v[46:47], v[46:47]
	v_pk_mul_f32 v[56:57], v[60:61], v[56:57]
	s_nop 0
	v_pk_mul_f32 v[60:61], v[48:49], v[56:57]
	v_pk_fma_f32 v[56:57], v[48:49], v[56:57], v[48:49] neg_lo:[1,0,0] neg_hi:[1,0,0]
	s_nop 0
	v_cndmask_b32_e32 v48, v56, v60, vcc
	v_cmp_gt_f32_e32 vcc, 0, v49
	v_and_b32_e32 v56, 0x7fffffff, v46
	s_nop 0
	v_cndmask_b32_e32 v49, v57, v61, vcc
	v_and_b32_e32 v57, 0x7fffffff, v47
	v_pk_fma_f32 v[56:57], v[56:57], s[90:91], 1.0 op_sel_hi:[1,0,0]
	v_cmp_gt_f32_e32 vcc, 0, v46
	v_rcp_f32_e32 v56, v56
	v_rcp_f32_e32 v57, v57
	s_nop 0
	v_pk_fma_f32 v[44:45], v[56:57], s[92:93], v[44:45] op_sel_hi:[1,0,0]
	s_nop 0
	v_pk_fma_f32 v[44:45], v[56:57], v[44:45], s[94:95] op_sel_hi:[1,1,0]
	s_nop 0
	v_pk_fma_f32 v[44:45], v[56:57], v[44:45], s[96:97] op_sel_hi:[1,1,0]
	s_nop 0
	v_pk_fma_f32 v[44:45], v[56:57], v[44:45], s[30:31] op_sel_hi:[1,1,0]
	s_nop 0
	v_pk_mul_f32 v[44:45], v[56:57], v[44:45]
	v_pk_mul_f32 v[56:57], v[58:59], s[2:3] op_sel_hi:[1,0]
	s_nop 0
	v_exp_f32_e32 v56, v56
	v_exp_f32_e32 v57, v57
	s_nop 0
	v_pk_mul_f32 v[44:45], v[56:57], v[44:45]
	s_nop 0
	v_pk_mul_f32 v[56:57], v[46:47], v[44:45]
	v_pk_fma_f32 v[44:45], v[46:47], v[44:45], v[46:47] neg_lo:[1,0,0] neg_hi:[1,0,0]
	s_nop 0
	v_cndmask_b32_e32 v46, v44, v56, vcc
	v_cmp_gt_f32_e32 vcc, 0, v47
	s_nop 1
	v_cndmask_b32_e32 v47, v45, v57, vcc

; __device__ __forceinline__ float ss_get(const ss_t* p) { const ss_t v = *p; return (float)(unsigned)(v >> 32) + (float)(unsigned)v * 2.3283064365386963e-10f; }
; __device__ __forceinline__ unsigned pkbf(float lo, float hi) { typedef float f2_t __attribute__((ext_vector_type(2))); typedef __bf16 b2_t __attribute__((ext_vector_type(2))); f2_t v = {lo, hi}; b2_t b = __builtin_convertvector(v, b2_t); return __builtin_bit_cast(unsigned, b); }
; __device__ __forceinline__ f32x2 gelu_pk(f32x2 v) {
;     const f32x2 av = __builtin_elementwise_abs(v), d = av * 0.2316418882f + 1.0f;
;     f32x2 t; t.x = __builtin_amdgcn_rcpf(d.x); t.y = __builtin_amdgcn_rcpf(d.y);
;     f32x2 q = t * 0.5307027145f + (-0.7265760135f); q = q * t + 0.7107068705f; q = q * t + (-0.142248368f); q = q * t + 0.127414796f; q = q * t;
;     const f32x2 s = (v * v) * (-0.72134752044f);
;     f32x2 e; e.x = __builtin_amdgcn_exp2f(s.x); e.y = __builtin_amdgcn_exp2f(s.y);
;     const f32x2 m = v * (q * e), r = v - m;
;     f32x2 o; o.x = v.x < 0.f ? m.x : r.x; o.y = v.y < 0.f ? m.y : r.y; return o;
; }
;     __device__ __forceinline__ void operator()(const f32x4 (&acc)[2][2][4][2], const Unit& u, int wr, int wc, int fr, int fq) const {
;     ...
;             for (int m = 0; m < 4; ++m) { const int row = row0 + ai * HALF + m * 16; bf16_t* rowp = O + (size_t)row * ldc + col0;
;                 const float rs = 1.0f / sqrtf(ss_get(ssq + row) * (1.0f / 2048.f) + 1e-6f);
; #pragma unroll
;                 for (int bj = 0; bj < 2; ++bj) { f32x4 v0 = acc[ai][bj][m][0] * rs, v1 = acc[ai][bj][m][1] * rs;
;                     if (act) { f32x2 a = gelu_pk((f32x2){v0[0], v0[1]}), b = gelu_pk((f32x2){v0[2], v0[3]}), c = gelu_pk((f32x2){v1[0], v1[1]}), d = gelu_pk((f32x2){v1[2], v1[3]});
;                         v0 = (f32x4){a.x, a.y, b.x, b.y}; v1 = (f32x4){c.x, c.y, d.x, d.y}; }
;                     u32x4 w; w.x = pkbf(v0[0], v0[1]); w.y = pkbf(v0[2], v0[3]); w.z = pkbf(v1[0], v1[1]); w.w = pkbf(v1[2], v1[3]);
;                     *(u32x4*)(rowp + bj * HALF) = w; } }
.LBB0_201:
	v_cvt_pk_bf16_f32 v40, v40, v41
	v_cvt_pk_bf16_f32 v41, v42, v43
	v_cvt_pk_bf16_f32 v42, v36, v37
	v_cvt_pk_bf16_f32 v43, v38, v39
	global_store_dwordx4 v[44:45], v[40:43], off offset:256
	s_nop 0
	v_mov_b32_e32 v39, v2
	v_mov_b32_e32 v36, v246
	s_nop 1
	s_nop 0
	s_nop 1
	s_nop 1
	s_nop 1
	s_and_b64 vcc, exec, s[36:37]
	v_pk_mul_f32 v[34:35], v[34:35], v[36:37] op_sel_hi:[1,0]
	v_pk_mul_f32 v[38:39], v[32:33], v[36:37] op_sel_hi:[1,0]
	v_pk_mul_f32 v[30:31], v[30:31], v[36:37] op_sel_hi:[1,0]
	v_pk_mul_f32 v[32:33], v[28:29], v[36:37] op_sel_hi:[1,0]
	s_cbranch_vccnz .LBB0_203
	v_and_b32_e32 v29, 0x7fffffff, v39
	v_and_b32_e32 v28, 0x7fffffff, v38
	v_pk_fma_f32 v[28:29], v[28:29], s[90:91], 1.0 op_sel_hi:[1,0,0]
	s_mov_b32 s2, 0xbf3a00e3
	v_rcp_f32_e32 v40, v28
	v_rcp_f32_e32 v41, v29
	v_mov_b64_e32 v[28:29], s[2:3]
	v_pk_mul_f32 v[44:45], v[38:39], v[38:39]
	s_mov_b32 s2, 0xbf38aa3b
	v_pk_fma_f32 v[42:43], v[40:41], s[92:93], v[28:29] op_sel_hi:[1,0,0]
	v_pk_mul_f32 v[44:45], v[44:45], s[2:3] op_sel_hi:[1,0]
	v_pk_fma_f32 v[42:43], v[40:41], v[42:43], s[94:95] op_sel_hi:[1,1,0]
	v_exp_f32_e32 v44, v44
	v_exp_f32_e32 v45, v45
	v_pk_fma_f32 v[42:43], v[40:41], v[42:43], s[96:97] op_sel_hi:[1,1,0]
	v_cmp_gt_f32_e32 vcc, 0, v38
	v_pk_fma_f32 v[42:43], v[40:41], v[42:43], s[30:31] op_sel_hi:[1,1,0]
	s_nop 0
	v_pk_mul_f32 v[40:41], v[40:41], v[42:43]
	v_pk_mul_f32 v[42:43], v[34:35], v[34:35]
	v_pk_mul_f32 v[40:41], v[44:45], v[40:41]
	v_pk_mul_f32 v[42:43], v[42:43], s[2:3] op_sel_hi:[1,0]
	v_pk_mul_f32 v[44:45], v[38:39], v[40:41]
	v_pk_fma_f32 v[40:41], v[38:39], v[40:41], v[38:39] neg_lo:[1,0,0] neg_hi:[1,0,0]
	v_exp_f32_e32 v42, v42
	v_cndmask_b32_e32 v38, v40, v44, vcc
	v_cmp_gt_f32_e32 vcc, 0, v39
	v_and_b32_e32 v40, 0x7fffffff, v34
	v_exp_f32_e32 v43, v43
	v_cndmask_b32_e32 v39, v41, v45, vcc
	v_and_b32_e32 v41, 0x7fffffff, v35
	v_pk_fma_f32 v[40:41], v[40:41], s[90:91], 1.0 op_sel_hi:[1,0,0]
	v_cmp_gt_f32_e32 vcc, 0, v34
	v_rcp_f32_e32 v40, v40
	v_rcp_f32_e32 v41, v41
	s_nop 0
	v_pk_fma_f32 v[44:45], v[40:41], s[92:93], v[28:29] op_sel_hi:[1,0,0]
	s_nop 0
	v_pk_fma_f32 v[44:45], v[40:41], v[44:45], s[94:95] op_sel_hi:[1,1,0]
	s_nop 0
	v_pk_fma_f32 v[44:45], v[40:41], v[44:45], s[96:97] op_sel_hi:[1,1,0]
	s_nop 0
	v_pk_fma_f32 v[44:45], v[40:41], v[44:45], s[30:31] op_sel_hi:[1,1,0]
	s_nop 0
	v_pk_mul_f32 v[40:41], v[40:41], v[44:45]
	v_pk_mul_f32 v[44:45], v[32:33], v[32:33]
	v_pk_mul_f32 v[40:41], v[42:43], v[40:41]
	v_pk_mul_f32 v[44:45], v[44:45], s[2:3] op_sel_hi:[1,0]
	v_pk_mul_f32 v[42:43], v[34:35], v[40:41]
	v_pk_fma_f32 v[40:41], v[34:35], v[40:41], v[34:35] neg_lo:[1,0,0] neg_hi:[1,0,0]
	v_exp_f32_e32 v44, v44
	v_cndmask_b32_e32 v34, v40, v42, vcc
	v_cmp_gt_f32_e32 vcc, 0, v35
	v_and_b32_e32 v40, 0x7fffffff, v32
	v_exp_f32_e32 v45, v45
	v_cndmask_b32_e32 v35, v41, v43, vcc
	v_and_b32_e32 v41, 0x7fffffff, v33
	v_pk_fma_f32 v[40:41], v[40:41], s[90:91], 1.0 op_sel_hi:[1,0,0]
	v_cmp_gt_f32_e32 vcc, 0, v32
	v_rcp_f32_e32 v40, v40
	v_rcp_f32_e32 v41, v41
	s_nop 0
	v_pk_fma_f32 v[42:43], v[40:41], s[92:93], v[28:29] op_sel_hi:[1,0,0]
	s_nop 0
	v_pk_fma_f32 v[42:43], v[40:41], v[42:43], s[94:95] op_sel_hi:[1,1,0]
	s_nop 0
	v_pk_fma_f32 v[42:43], v[40:41], v[42:43], s[96:97] op_sel_hi:[1,1,0]
	s_nop 0
	v_pk_fma_f32 v[42:43], v[40:41], v[42:43], s[30:31] op_sel_hi:[1,1,0]
	s_nop 0
	v_pk_mul_f32 v[40:41], v[40:41], v[42:43]
	v_pk_mul_f32 v[42:43], v[30:31], v[30:31]
	v_pk_mul_f32 v[40:41], v[44:45], v[40:41]
	s_nop 0
	v_pk_mul_f32 v[44:45], v[32:33], v[40:41]
	v_pk_fma_f32 v[40:41], v[32:33], v[40:41], v[32:33] neg_lo:[1,0,0] neg_hi:[1,0,0]
	s_nop 0
	v_cndmask_b32_e32 v32, v40, v44, vcc
	v_cmp_gt_f32_e32 vcc, 0, v33
	v_and_b32_e32 v40, 0x7fffffff, v30
	s_nop 0
	v_cndmask_b32_e32 v33, v41, v45, vcc
	v_and_b32_e32 v41, 0x7fffffff, v31
	v_pk_fma_f32 v[40:41], v[40:41], s[90:91], 1.0 op_sel_hi:[1,0,0]
	v_cmp_gt_f32_e32 vcc, 0, v30
	v_rcp_f32_e32 v40, v40
	v_rcp_f32_e32 v41, v41
	s_nop 0
	v_pk_fma_f32 v[28:29], v[40:41], s[92:93], v[28:29] op_sel_hi:[1,0,0]
	s_nop 0
	v_pk_fma_f32 v[28:29], v[40:41], v[28:29], s[94:95] op_sel_hi:[1,1,0]
	s_nop 0
	v_pk_fma_f32 v[28:29], v[40:41], v[28:29], s[96:97] op_sel_hi:[1,1,0]
	s_nop 0
	v_pk_fma_f32 v[28:29], v[40:41], v[28:29], s[30:31] op_sel_hi:[1,1,0]
	s_nop 0
	v_pk_mul_f32 v[28:29], v[40:41], v[28:29]
	v_pk_mul_f32 v[40:41], v[42:43], s[2:3] op_sel_hi:[1,0]
	s_nop 0
	v_exp_f32_e32 v40, v40
	v_exp_f32_e32 v41, v41
	s_nop 0
	v_pk_mul_f32 v[28:29], v[40:41], v[28:29]
	s_nop 0
	v_pk_mul_f32 v[40:41], v[30:31], v[28:29]
	v_pk_fma_f32 v[28:29], v[30:31], v[28:29], v[30:31] neg_lo:[1,0,0] neg_hi:[1,0,0]
	s_nop 0
	v_cndmask_b32_e32 v30, v28, v40, vcc
	v_cmp_gt_f32_e32 vcc, 0, v31
	s_nop 1
	v_cndmask_b32_e32 v31, v29, v41, vcc

; __device__ __forceinline__ float ss_get(const ss_t* p) { const ss_t v = *p; return (float)(unsigned)(v >> 32) + (float)(unsigned)v * 2.3283064365386963e-10f; }
; __device__ __forceinline__ unsigned pkbf(float lo, float hi) { typedef float f2_t __attribute__((ext_vector_type(2))); typedef __bf16 b2_t __attribute__((ext_vector_type(2))); f2_t v = {lo, hi}; b2_t b = __builtin_convertvector(v, b2_t); return __builtin_bit_cast(unsigned, b); }
; __device__ __forceinline__ f32x2 gelu_pk(f32x2 v) {
;     const f32x2 av = __builtin_elementwise_abs(v), d = av * 0.2316418882f + 1.0f;
;     f32x2 t; t.x = __builtin_amdgcn_rcpf(d.x); t.y = __builtin_amdgcn_rcpf(d.y);
;     f32x2 q = t * 0.5307027145f + (-0.7265760135f); q = q * t + 0.7107068705f; q = q * t + (-0.142248368f); q = q * t + 0.127414796f; q = q * t;
;     const f32x2 s = (v * v) * (-0.72134752044f);
;     f32x2 e; e.x = __builtin_amdgcn_exp2f(s.x); e.y = __builtin_amdgcn_exp2f(s.y);
;     const f32x2 m = v * (q * e), r = v - m;
;     f32x2 o; o.x = v.x < 0.f ? m.x : r.x; o.y = v.y < 0.f ? m.y : r.y; return o;
; }
;     __device__ __forceinline__ void operator()(const f32x4 (&acc)[2][2][4][2], const Unit& u, int wr, int wc, int fr, int fq) const {
;     ...
;             for (int m = 0; m < 4; ++m) { const int row = row0 + ai * HALF + m * 16; bf16_t* rowp = O + (size_t)row * ldc + col0;
;                 const float rs = 1.0f / sqrtf(ss_get(ssq + row) * (1.0f / 2048.f) + 1e-6f);
; #pragma unroll
;                 for (int bj = 0; bj < 2; ++bj) { f32x4 v0 = acc[ai][bj][m][0] * rs, v1 = acc[ai][bj][m][1] * rs;
;                     if (act) { f32x2 a = gelu_pk((f32x2){v0[0], v0[1]}), b = gelu_pk((f32x2){v0[2], v0[3]}), c = gelu_pk((f32x2){v1[0], v1[1]}), d = gelu_pk((f32x2){v1[2], v1[3]});
;                         v0 = (f32x4){a.x, a.y, b.x, b.y}; v1 = (f32x4){c.x, c.y, d.x, d.y}; }
;                     u32x4 w; w.x = pkbf(v0[0], v0[1]); w.y = pkbf(v0[2], v0[3]); w.z = pkbf(v1[0], v1[1]); w.w = pkbf(v1[2], v1[3]);
;                     *(u32x4*)(rowp + bj * HALF) = w; } }
.LBB0_205:
	v_cvt_pk_bf16_f32 v24, v24, v25
	v_cvt_pk_bf16_f32 v25, v26, v27
	v_cvt_pk_bf16_f32 v26, v20, v21
	v_cvt_pk_bf16_f32 v27, v22, v23
	global_store_dwordx4 v[28:29], v[24:27], off offset:256
	s_nop 0
	v_mov_b32_e32 v23, v2
	v_mov_b32_e32 v20, v252
	s_nop 1
	s_nop 0
	s_nop 1
	s_nop 1
	s_nop 1
	s_and_b64 vcc, exec, s[36:37]
	v_pk_mul_f32 v[18:19], v[18:19], v[20:21] op_sel_hi:[1,0]
	v_pk_mul_f32 v[22:23], v[16:17], v[20:21] op_sel_hi:[1,0]
	v_pk_mul_f32 v[14:15], v[14:15], v[20:21] op_sel_hi:[1,0]
	v_pk_mul_f32 v[16:17], v[12:13], v[20:21] op_sel_hi:[1,0]
	s_cbranch_vccnz .LBB0_207
	v_and_b32_e32 v13, 0x7fffffff, v23
	v_and_b32_e32 v12, 0x7fffffff, v22
	v_pk_fma_f32 v[12:13], v[12:13], s[90:91], 1.0 op_sel_hi:[1,0,0]
	s_mov_b32 s2, 0xbf3a00e3
	v_rcp_f32_e32 v24, v12
	v_rcp_f32_e32 v25, v13
	v_mov_b64_e32 v[12:13], s[2:3]
	v_pk_mul_f32 v[28:29], v[22:23], v[22:23]
	s_mov_b32 s2, 0xbf38aa3b
	v_pk_fma_f32 v[26:27], v[24:25], s[92:93], v[12:13] op_sel_hi:[1,0,0]
	v_pk_mul_f32 v[28:29], v[28:29], s[2:3] op_sel_hi:[1,0]
	v_pk_fma_f32 v[26:27], v[24:25], v[26:27], s[94:95] op_sel_hi:[1,1,0]
	v_exp_f32_e32 v28, v28
	v_exp_f32_e32 v29, v29
	v_pk_fma_f32 v[26:27], v[24:25], v[26:27], s[96:97] op_sel_hi:[1,1,0]
	v_cmp_gt_f32_e32 vcc, 0, v22
	v_pk_fma_f32 v[26:27], v[24:25], v[26:27], s[30:31] op_sel_hi:[1,1,0]
	s_nop 0
	v_pk_mul_f32 v[24:25], v[24:25], v[26:27]
	v_pk_mul_f32 v[26:27], v[18:19], v[18:19]
	v_pk_mul_f32 v[24:25], v[28:29], v[24:25]
	v_pk_mul_f32 v[26:27], v[26:27], s[2:3] op_sel_hi:[1,0]
	v_pk_mul_f32 v[28:29], v[22:23], v[24:25]
	v_pk_fma_f32 v[24:25], v[22:23], v[24:25], v[22:23] neg_lo:[1,0,0] neg_hi:[1,0,0]
	v_exp_f32_e32 v26, v26
	v_cndmask_b32_e32 v22, v24, v28, vcc
	v_cmp_gt_f32_e32 vcc, 0, v23
	v_and_b32_e32 v24, 0x7fffffff, v18
	v_exp_f32_e32 v27, v27
	v_cndmask_b32_e32 v23, v25, v29, vcc
	v_and_b32_e32 v25, 0x7fffffff, v19
	v_pk_fma_f32 v[24:25], v[24:25], s[90:91], 1.0 op_sel_hi:[1,0,0]
	v_cmp_gt_f32_e32 vcc, 0, v18
	v_rcp_f32_e32 v24, v24
	v_rcp_f32_e32 v25, v25
	s_nop 0
	v_pk_fma_f32 v[28:29], v[24:25], s[92:93], v[12:13] op_sel_hi:[1,0,0]
	s_nop 0
	v_pk_fma_f32 v[28:29], v[24:25], v[28:29], s[94:95] op_sel_hi:[1,1,0]
	s_nop 0
	v_pk_fma_f32 v[28:29], v[24:25], v[28:29], s[96:97] op_sel_hi:[1,1,0]
	s_nop 0
	v_pk_fma_f32 v[28:29], v[24:25], v[28:29], s[30:31] op_sel_hi:[1,1,0]
	s_nop 0
	v_pk_mul_f32 v[24:25], v[24:25], v[28:29]
	v_pk_mul_f32 v[28:29], v[16:17], v[16:17]
	v_pk_mul_f32 v[24:25], v[26:27], v[24:25]
	v_pk_mul_f32 v[28:29], v[28:29], s[2:3] op_sel_hi:[1,0]
	v_pk_mul_f32 v[26:27], v[18:19], v[24:25]
	v_pk_fma_f32 v[24:25], v[18:19], v[24:25], v[18:19] neg_lo:[1,0,0] neg_hi:[1,0,0]
	v_exp_f32_e32 v28, v28
	v_cndmask_b32_e32 v18, v24, v26, vcc
	v_cmp_gt_f32_e32 vcc, 0, v19
	v_and_b32_e32 v24, 0x7fffffff, v16
	v_exp_f32_e32 v29, v29
	v_cndmask_b32_e32 v19, v25, v27, vcc
	v_and_b32_e32 v25, 0x7fffffff, v17
	v_pk_fma_f32 v[24:25], v[24:25], s[90:91], 1.0 op_sel_hi:[1,0,0]
	v_cmp_gt_f32_e32 vcc, 0, v16
	v_rcp_f32_e32 v24, v24
	v_rcp_f32_e32 v25, v25
	s_nop 0
	v_pk_fma_f32 v[26:27], v[24:25], s[92:93], v[12:13] op_sel_hi:[1,0,0]
	s_nop 0
	v_pk_fma_f32 v[26:27], v[24:25], v[26:27], s[94:95] op_sel_hi:[1,1,0]
	s_nop 0
	v_pk_fma_f32 v[26:27], v[24:25], v[26:27], s[96:97] op_sel_hi:[1,1,0]
	s_nop 0
	v_pk_fma_f32 v[26:27], v[24:25], v[26:27], s[30:31] op_sel_hi:[1,1,0]
	s_nop 0
	v_pk_mul_f32 v[24:25], v[24:25], v[26:27]
	v_pk_mul_f32 v[26:27], v[14:15], v[14:15]
	v_pk_mul_f32 v[24:25], v[28:29], v[24:25]
	s_nop 0
	v_pk_mul_f32 v[28:29], v[16:17], v[24:25]
	v_pk_fma_f32 v[24:25], v[16:17], v[24:25], v[16:17] neg_lo:[1,0,0] neg_hi:[1,0,0]
	s_nop 0
	v_cndmask_b32_e32 v16, v24, v28, vcc
	v_cmp_gt_f32_e32 vcc, 0, v17
	v_and_b32_e32 v24, 0x7fffffff, v14
	s_nop 0
	v_cndmask_b32_e32 v17, v25, v29, vcc
	v_and_b32_e32 v25, 0x7fffffff, v15
	v_pk_fma_f32 v[24:25], v[24:25], s[90:91], 1.0 op_sel_hi:[1,0,0]
	v_cmp_gt_f32_e32 vcc, 0, v14
	v_rcp_f32_e32 v24, v24
	v_rcp_f32_e32 v25, v25
	s_nop 0
	v_pk_fma_f32 v[12:13], v[24:25], s[92:93], v[12:13] op_sel_hi:[1,0,0]
	s_nop 0
	v_pk_fma_f32 v[12:13], v[24:25], v[12:13], s[94:95] op_sel_hi:[1,1,0]
	s_nop 0
	v_pk_fma_f32 v[12:13], v[24:25], v[12:13], s[96:97] op_sel_hi:[1,1,0]
	s_nop 0
	v_pk_fma_f32 v[12:13], v[24:25], v[12:13], s[30:31] op_sel_hi:[1,1,0]
	s_nop 0
	v_pk_mul_f32 v[12:13], v[24:25], v[12:13]
	v_pk_mul_f32 v[24:25], v[26:27], s[2:3] op_sel_hi:[1,0]
	s_nop 0
	v_exp_f32_e32 v24, v24
	v_exp_f32_e32 v25, v25
	s_nop 0
	v_pk_mul_f32 v[12:13], v[24:25], v[12:13]
	s_nop 0
	v_pk_mul_f32 v[24:25], v[14:15], v[12:13]
	v_pk_fma_f32 v[12:13], v[14:15], v[12:13], v[14:15] neg_lo:[1,0,0] neg_hi:[1,0,0]
	s_nop 0
	v_cndmask_b32_e32 v14, v12, v24, vcc
	v_cmp_gt_f32_e32 vcc, 0, v15
	s_nop 1
	v_cndmask_b32_e32 v15, v13, v25, vcc

; __device__ __forceinline__ float ss_get(const ss_t* p) { const ss_t v = *p; return (float)(unsigned)(v >> 32) + (float)(unsigned)v * 2.3283064365386963e-10f; }
; #define PG8_STAGE(bufoff, gbase, voff) do { _Pragma("unroll") for (int _i = 0; _i < 2; ++_i) \
;         __builtin_amdgcn_global_load_lds((const unsigned*)((const char*)(gbase) + (voff)[_i]), (PG8_LAS unsigned*)(lds + (bufoff) + ldsw + _i * 8192), 16, 0, 0); } while (0)
; #define PG8_BAR __builtin_amdgcn_s_barrier()
;     __device__ __forceinline__ void operator()(const f32x4 (&acc)[2][2][4][2], const Unit& u, int wr, int wc, int fr, int fq) const {
;     ...
;                 const float rs = 1.0f / sqrtf(ss_get(ssq + row) * (1.0f / 2048.f) + 1e-6f);
; template <class Epi, class Sched, bool ALIGN_EPI = false, bool SP2 = false>
; __device__ __forceinline__ void gemm_phase(PG8_LAS unsigned char* lds, const Gemm g, const Sched& S, const Epi& E) {
;     ...
;     for (int i = 0; i < 2; ++i) { int R, C; stage_rc(tid * 16 + i * 8192, R, C); const int Rb = Epi::PERM ? ((R & ~31) + perm32(R & 31)) : R;
;         voffA[i] = (unsigned)(R * K + C) * 2u; voffB[i] = (unsigned)(Rb * K + C) * 2u; }
;     const size_t kstep = (size_t)(BK * 2);
;     const size_t hstep = (size_t)HALF * K * 2;
;     const size_t tstep = 2 * hstep;
;     const unsigned ldsw = (unsigned)wid * 1024u;
;     const int aoff = lds_byte(wr * 64 + fr, fq * 8), boff = lds_byte(wc * 32 + fr, fq * 8);
;     ...
;     Unit cur, nxt; int ui = 0;
;     if (!S.next(0, cur)) return;
;     f32x4 acc[2][2][4][2];
; #pragma unroll
;     for (int a = 0; a < 2; ++a)
; #pragma unroll
;         for (int b = 0; b < 2; ++b)
; #pragma unroll
;             for (int m = 0; m < 4; ++m)
; #pragma unroll
;                 for (int n = 0; n < 2; ++n) acc[a][b][m][n] = (f32x4){0.f, 0.f, 0.f, 0.f};
;     bf16x8 At[4][2], B0[2][2], B1[2][2];
;     const char* cA = (const char*)g.A + (size_t)cur.pm * tstep; const char* cB = (const char*)g.Bt + (size_t)cur.pn * tstep;
;     S.a_ready(cur);
;     if constexpr (SP2) {
;         PG8_STAGE(PG8_SB(0, 0), cB, voffB); PG8_STAGE(PG8_SB(0, 1), cB + hstep, voffB); PG8_STAGE(PG8_SA(0, 0), cA, voffA); PG8_STAGE(PG8_SA(0, 1), cA + hstep, voffA);
;         if (wr == 1) PG8_BAR;
;         PG8_WAIT_V(2); PG8_BAR;
;         PG8_STAGE(PG8_SB(1, 0), cB + kstep, voffB); PG8_STAGE(PG8_SA(1, 0), cA + kstep, voffA); PG8_STAGE(PG8_SB(1, 1), cB + hstep + kstep, voffB);
.LBB0_1043:
	s_andn2_b64 vcc, exec, s[2:3]
	s_cbranch_vccnz .LBB0_1058
	v_readlane_b32 s2, v248, 27
	v_mov_b32_e32 v3, v204
	v_readlane_b32 s3, v248, 28
	s_andn2_b64 vcc, exec, s[2:3]
	v_readfirstlane_b32 s2, v3
	s_cbranch_vccnz .LBB0_1058
	v_readlane_b32 s100, v250, 59
	v_bfe_u32 v252, v204, 8, 1
	v_and_b32_e32 v253, 15, v204
	v_lshl_or_b32 v252, v252, 6, v253
	v_add_u32_e32 v252, s100, v252
	v_mov_b32_e32 v253, 0
	v_lshl_add_u64 v[252:253], v[252:253], 3, s[4:5]
	global_load_dwordx2 v[172:173], v[252:253], off
	global_load_dwordx2 v[174:175], v[252:253], off offset:128
	global_load_dwordx2 v[176:177], v[252:253], off offset:256
	global_load_dwordx2 v[178:179], v[252:253], off offset:384
	global_load_dwordx2 v[180:181], v[252:253], off offset:1024
	global_load_dwordx2 v[182:183], v[252:253], off offset:1152
	global_load_dwordx2 v[184:185], v[252:253], off offset:1280
	global_load_dwordx2 v[186:187], v[252:253], off offset:1408
	v_lshlrev_b32_e32 v1, 4, v3
	v_add_u32_e32 v0, 0x2000, v1
	v_ashrrev_i32_e32 v4, 31, v0
	v_lshrrev_b32_e32 v4, 22, v4
	v_add_u32_e32 v4, v0, v4
	v_ashrrev_i32_e32 v8, 10, v4
	v_mul_i32_i24_e32 v4, 0x400, v8
	v_sub_u32_e32 v0, v0, v4
	v_lshrrev_b32_e32 v4, 4, v0
	v_bitop3_b32 v0, v4, v0, 32 bitop3:0x6c
	v_ashrrev_i32_e32 v4, 31, v0
	v_lshrrev_b32_e32 v4, 26, v4
	v_add_u32_e32 v4, v0, v4
	v_lshlrev_b32_e32 v5, 3, v8
	v_ashrrev_i32_e32 v9, 6, v4
	v_and_b32_e32 v5, -16, v5
	v_add_u32_e32 v5, v9, v5
	v_and_b32_e32 v6, 3, v9
	s_mov_b32 s6, 0xfffe0
	v_lshrrev_b32_e32 v7, 2, v5
	v_lshlrev_b32_e32 v10, 1, v5
	v_and_b32_e32 v4, 0xc0, v4
	v_and_or_b32 v6, v5, s6, v6
	v_and_b32_e32 v7, 4, v7
	v_and_b32_e32 v10, 24, v10
	v_sub_u32_e32 v0, v0, v4
	v_or3_b32 v6, v6, v7, v10
	v_lshlrev_b32_e32 v7, 5, v8
	v_ashrrev_i16_sdwa v0, v207, sext(v0) dst_sel:DWORD dst_unused:UNUSED_PAD src0_sel:DWORD src1_sel:BYTE_0
	v_and_b32_e32 v7, 32, v7
	v_bfe_i32 v10, v0, 0, 16
	v_add_lshl_u32 v4, v7, v10, 1
	v_lshl_add_u32 v0, v6, 12, v4
	v_lshl_add_u32 v132, v5, 12, v4
	v_bfe_i32 v4, v3, 27, 1
	v_lshrrev_b32_e32 v4, 22, v4
	v_add_u32_e32 v4, v1, v4
	v_and_b32_e32 v4, 0xfffffc00, v4
	v_sub_u32_e32 v1, v1, v4
	v_lshrrev_b32_e32 v4, 4, v1
	v_ashrrev_i32_e32 v5, 31, v3
	v_bitop3_b32 v1, v4, v1, 32 bitop3:0x6c
	v_lshrrev_b32_e32 v5, 26, v5
	v_ashrrev_i32_e32 v4, 31, v1
	v_add_u32_e32 v5, v3, v5
	v_lshrrev_b32_e32 v4, 26, v4
	v_ashrrev_i32_e32 v12, 6, v5
	v_add_u32_e32 v4, v1, v4
	v_lshlrev_b32_e32 v5, 3, v12
	v_ashrrev_i32_e32 v11, 6, v4
	v_and_b32_e32 v5, -16, v5
	v_add_u32_e32 v5, v11, v5
	v_and_b32_e32 v6, 3, v11
	v_lshrrev_b32_e32 v7, 2, v5
	v_lshlrev_b32_e32 v13, 1, v5
	v_and_b32_e32 v4, 0xc0, v4
	s_ashr_i32 s3, s2, 6
	v_and_or_b32 v6, v5, s6, v6
	v_and_b32_e32 v7, 4, v7
	v_and_b32_e32 v13, 24, v13
	v_sub_u32_e32 v1, v1, v4
	s_ashr_i32 s10, s2, 8
	s_lshl_b32 s42, s3, 10
	v_or3_b32 v6, v6, v7, v13
	v_lshlrev_b32_e32 v7, 5, v12
	v_ashrrev_i16_sdwa v1, v207, sext(v1) dst_sel:DWORD dst_unused:UNUSED_PAD src0_sel:DWORD src1_sel:BYTE_0
	v_readlane_b32 s6, v248, 31
	v_and_b32_e32 v7, 32, v7
	v_bfe_i32 v13, v1, 0, 16
	v_readlane_b32 s7, v248, 32
	s_add_u32 s6, s46, s6
	v_add_lshl_u32 v1, v7, v13, 1
	s_addc_u32 s7, s47, s7
	s_add_i32 s43, s42, 0
	v_lshl_add_u32 v134, v6, 12, v1
	s_add_i32 m0, s43, 0x10000
	v_lshl_add_u32 v136, v5, 12, v1
	global_load_lds_dwordx4 v134, s[6:7]
	s_add_i32 m0, s43, 0x12000
	s_add_u32 s8, s6, 0x80000
	global_load_lds_dwordx4 v0, s[6:7]
	s_addc_u32 s9, s7, 0
	s_add_i32 m0, s43, 0x14000
	s_add_i32 s44, s43, 0x2000
	global_load_lds_dwordx4 v134, s[8:9]
	s_add_i32 m0, s43, 0x16000
	s_add_i32 s45, s43, 0x4000
	global_load_lds_dwordx4 v0, s[8:9]
	s_mov_b32 m0, s43
	v_readlane_b32 s8, v250, 57
	global_load_lds_dwordx4 v136, s[0:1]
	s_mov_b32 m0, s44
	v_readlane_b32 s9, v250, 58
	global_load_lds_dwordx4 v132, s[0:1]
	s_mov_b32 m0, s45
	s_add_i32 s48, s43, 0x6000
	v_mov_b32_e32 v135, v2
	s_nop 0
	global_load_lds_dwordx4 v136, s[8:9]
	s_mov_b32 m0, s48
	v_mov_b32_e32 v1, v2
	global_load_lds_dwordx4 v132, s[8:9]
	s_cmp_eq_u32 s10, 1
	v_lshl_add_u64 v[4:5], s[6:7], 0, v[134:135]
	s_cselect_b64 s[8:9], -1, 0
	s_cmp_lg_u32 s10, 1
	v_lshl_add_u64 v[6:7], s[6:7], 0, v[0:1]
	s_cbranch_scc1 .LBB0_1047
	s_barrier
; __device__ __forceinline__ float ss_get(const ss_t* p) { const ss_t v = *p; return (float)(unsigned)(v >> 32) + (float)(unsigned)v * 2.3283064365386963e-10f; }
; #define PG8_STAGE(bufoff, gbase, voff) do { _Pragma("unroll") for (int _i = 0; _i < 2; ++_i) \
;         __builtin_amdgcn_global_load_lds((const unsigned*)((const char*)(gbase) + (voff)[_i]), (PG8_LAS unsigned*)(lds + (bufoff) + ldsw + _i * 8192), 16, 0, 0); } while (0)
; #define PG8_WAIT_V(n) asm volatile("s_waitcnt vmcnt(" #n ")" ::: "memory")
; #define PG8_BAR __builtin_amdgcn_s_barrier()
;     __device__ __forceinline__ void operator()(const f32x4 (&acc)[2][2][4][2], const Unit& u, int wr, int wc, int fr, int fq) const {
;     ...
;                 const float rs = 1.0f / sqrtf(ss_get(ssq + row) * (1.0f / 2048.f) + 1e-6f);
; template <class Epi, class Sched, bool ALIGN_EPI = false, bool SP2 = false>
; __device__ __forceinline__ void gemm_phase(PG8_LAS unsigned char* lds, const Gemm g, const Sched& S, const Epi& E) {
;     ...
;         PG8_STAGE(PG8_SB(0, 0), cB, voffB); PG8_STAGE(PG8_SB(0, 1), cB + hstep, voffB); PG8_STAGE(PG8_SA(0, 0), cA, voffA); PG8_STAGE(PG8_SA(0, 1), cA + hstep, voffA);
;         if (wr == 1) PG8_BAR;
;         PG8_WAIT_V(2); PG8_BAR;
;         PG8_STAGE(PG8_SB(1, 0), cB + kstep, voffB); PG8_STAGE(PG8_SA(1, 0), cA + kstep, voffA); PG8_STAGE(PG8_SB(1, 1), cB + hstep + kstep, voffB);
;         PG8_WAIT_V(6); PG8_BAR;
.LBB0_1047:
	v_lshrrev_b32_e32 v20, 1, v3
	v_and_b32_e32 v20, 24, v20
	v_and_b32_e32 v18, 15, v3
	v_lshlrev_b32_e32 v21, 1, v20
	v_lshlrev_b32_e32 v3, 2, v3
	s_lshl_b32 s3, s3, 5
	v_mov_b32_e32 v137, v2
	v_lshl_or_b32 v19, s10, 6, v18
	v_lshl_or_b32 v18, v18, 6, v21
	s_lshl_b32 s10, s10, 13
	v_and_b32_e32 v3, 32, v3
	s_and_b32 s3, s3, 0x60
	s_add_i32 m0, s43, 0x18000
	v_lshl_add_u64 v[4:5], v[4:5], 0, s[28:29]
	v_lshl_add_u64 v[14:15], s[0:1], 0, v[136:137]
	v_mov_b32_e32 v133, v2
	v_bitop3_b32 v21, v18, s10, v3 bitop3:0xde
	s_lshl_b32 s10, s3, 7
	s_waitcnt vmcnt(2)
	s_barrier
	global_load_lds_dwordx4 v[4:5], off
	v_lshl_add_u64 v[4:5], v[6:7], 0, s[28:29]
	s_add_i32 m0, s43, 0x1a000
	s_add_i32 s49, s43, 0x8000
	s_add_i32 s50, s43, 0xa000
	v_lshl_add_u64 v[16:17], s[0:1], 0, v[132:133]
	v_bitop3_b32 v3, v18, s10, v3 bitop3:0xde
	global_load_lds_dwordx4 v[4:5], off
	v_lshl_add_u64 v[4:5], v[14:15], 0, s[28:29]
	s_mov_b32 m0, s49
	s_add_u32 s10, s6, 0x80080
	global_load_lds_dwordx4 v[4:5], off
	v_lshl_add_u64 v[4:5], v[16:17], 0, s[28:29]
	s_mov_b32 m0, s50
	s_addc_u32 s11, s7, 0
	global_load_lds_dwordx4 v[4:5], off
	s_add_i32 m0, s43, 0x1c000
	v_lshl_add_u64 v[4:5], s[10:11], 0, v[134:135]
	global_load_lds_dwordx4 v[4:5], off
	v_lshl_add_u64 v[4:5], s[10:11], 0, v[0:1]
	s_add_i32 m0, s43, 0x1e000
	s_cmpk_lt_u32 s2, 0x100
	global_load_lds_dwordx4 v[4:5], off
	v_lshlrev_b32_e32 v4, 15, v12
	v_and_b32_e32 v4, 0xffff0000, v4
	v_readlane_b32 s2, v250, 59
	v_lshl_add_u32 v4, v11, 12, v4
	v_and_b32_e32 v5, 1, v12
	v_add_u32_e32 v148, s2, v19
	v_or_b32_e32 v149, s3, v20
	v_lshl_or_b32 v4, v5, 6, v4
	v_readlane_b32 s2, v247, 10
	v_lshl_add_u32 v4, v13, 1, v4
	v_mov_b32_e32 v5, v2
	v_readlane_b32 s3, v247, 11
	s_waitcnt vmcnt(6)
	s_cselect_b64 s[10:11], -1, 0
	v_cvt_f32_u32_e32 v188, v173
	v_cvt_f32_u32_e32 v189, v172
	v_fmac_f32_e32 v188, 0x2f800000, v189
	v_fmamk_f32 v188, v188, 0x3a000000, v205
	v_rsq_f32_e32 v240, v188
	v_cvt_f32_u32_e32 v188, v175
	v_cvt_f32_u32_e32 v189, v174
	v_fmac_f32_e32 v188, 0x2f800000, v189
	v_fmamk_f32 v188, v188, 0x3a000000, v205
	v_rsq_f32_e32 v241, v188
	v_cvt_f32_u32_e32 v188, v177
	v_cvt_f32_u32_e32 v189, v176
	v_fmac_f32_e32 v188, 0x2f800000, v189
	v_fmamk_f32 v188, v188, 0x3a000000, v205
	v_rsq_f32_e32 v242, v188
	v_cvt_f32_u32_e32 v188, v179
	v_cvt_f32_u32_e32 v189, v178
	v_fmac_f32_e32 v188, 0x2f800000, v189
	v_fmamk_f32 v188, v188, 0x3a000000, v205
	v_rsq_f32_e32 v243, v188
	v_cvt_f32_u32_e32 v188, v181
	v_cvt_f32_u32_e32 v189, v180
	v_fmac_f32_e32 v188, 0x2f800000, v189
	v_fmamk_f32 v188, v188, 0x3a000000, v205
	v_rsq_f32_e32 v244, v188
	v_cvt_f32_u32_e32 v188, v183
	v_cvt_f32_u32_e32 v189, v182
	v_fmac_f32_e32 v188, 0x2f800000, v189
	v_fmamk_f32 v188, v188, 0x3a000000, v205
	v_rsq_f32_e32 v245, v188
	v_cvt_f32_u32_e32 v188, v185
	v_cvt_f32_u32_e32 v189, v184
	v_fmac_f32_e32 v188, 0x2f800000, v189
	v_fmamk_f32 v188, v188, 0x3a000000, v205
	v_rsq_f32_e32 v246, v188
	v_cvt_f32_u32_e32 v188, v187
	v_cvt_f32_u32_e32 v189, v186
	v_fmac_f32_e32 v188, 0x2f800000, v189
	v_fmamk_f32 v188, v188, 0x3a000000, v205
	v_rsq_f32_e32 v252, v188
	s_nop 0
	s_mov_b32 s51, 0
	v_lshl_add_u64 v[138:139], s[2:3], 0, v[4:5]
	v_lshlrev_b32_e32 v4, 15, v8
	v_and_b32_e32 v4, 0xffff0000, v4
	v_lshl_add_u32 v4, v9, 12, v4
	v_and_b32_e32 v5, 1, v8
	v_lshl_or_b32 v4, v5, 6, v4
	v_lshl_add_u32 v4, v10, 1, v4
	v_mov_b32_e32 v5, v2
	v_lshl_add_u64 v[140:141], s[2:3], 0, v[4:5]
	v_add_u32_e32 v150, 0, v21
	v_readlane_b32 s12, v248, 29
	s_barrier
	v_readlane_b32 s13, v248, 30
	s_branch .LBB0_1050

; __device__ __forceinline__ float ss_get(const ss_t* p) { const ss_t v = *p; return (float)(unsigned)(v >> 32) + (float)(unsigned)v * 2.3283064365386963e-10f; }
; __device__ __forceinline__ unsigned pkbf(float lo, float hi) { typedef float f2_t __attribute__((ext_vector_type(2))); typedef __bf16 b2_t __attribute__((ext_vector_type(2))); f2_t v = {lo, hi}; b2_t b = __builtin_convertvector(v, b2_t); return __builtin_bit_cast(unsigned, b); }
; __device__ __forceinline__ f32x2 swiglu_pk(f32x2 g, f32x2 u, float c1, float rs2) {
;     const f32x2 z = g * c1; f32x2 e; e.x = __builtin_amdgcn_exp2f(z.x); e.y = __builtin_amdgcn_exp2f(z.y);
;     const f32x2 d = e + 1.0f; f32x2 r; r.x = __builtin_amdgcn_rcpf(d.x); r.y = __builtin_amdgcn_rcpf(d.y);
;     return (g * u) * (r * rs2);
; }
;     __device__ __forceinline__ void operator()(const f32x4 (&acc)[2][2][4][2], const Unit& u, int wr, int wc, int fr, int fq) const {
;     ...
;             for (int m = 0; m < 4; ++m) { const int row = row0 + ai * HALF + m * 16; bf16_t* rowp = O + (size_t)row * ldc + col0;
;                 const float rs = 1.0f / sqrtf(ss_get(ssq + row) * (1.0f / 2048.f) + 1e-6f);
;                 const float c1 = -1.4426950408889634f * rs, rs2 = rs * rs;
;                 const f32x4 ga = acc[ai][0][m][0], gb = acc[ai][0][m][1], ua = acc[ai][1][m][0], ub = acc[ai][1][m][1];
;                 u32x4 w;
;                 { const f32x2 o = swiglu_pk((f32x2){ga[0], ga[1]}, (f32x2){ua[0], ua[1]}, c1, rs2); w.x = pkbf(o.x, o.y); }
;                 { const f32x2 o = swiglu_pk((f32x2){ga[2], ga[3]}, (f32x2){ua[2], ua[3]}, c1, rs2); w.y = pkbf(o.x, o.y); }
;                 { const f32x2 o = swiglu_pk((f32x2){gb[0], gb[1]}, (f32x2){ub[0], ub[1]}, c1, rs2); w.z = pkbf(o.x, o.y); }
;                 { const f32x2 o = swiglu_pk((f32x2){gb[2], gb[3]}, (f32x2){ub[2], ub[3]}, c1, rs2); w.w = pkbf(o.x, o.y); }
;                 *(u32x4*)rowp = w; }
.LBB0_1054:
	v_mov_b32_e32 v142, v148
	v_readlane_b32 s2, v247, 4
	v_ashrrev_i32_e32 v143, 31, v142
	v_lshl_add_u64 v[146:147], v[142:143], 3, s[4:5]
	v_readlane_b32 s3, v247, 5
	v_mov_b32_e32 v157, v2
	v_pk_mul_f32 v[158:159], v[116:117], v[124:125]
	v_mov_b64_e32 v[144:145], s[2:3]
	s_flbit_i32_b32 s2, 0
	s_min_u32 s13, s2, 32
	s_sub_i32 s36, 32, s13
	v_lshl_or_b32 v154, s52, 7, v149
	v_ashrrev_i32_e32 v155, 31, v154
	s_movk_i32 s16, 0x2c00
	v_pk_mul_f32 v[130:131], v[122:123], v[130:131]
	v_pk_mul_f32 v[128:129], v[120:121], v[128:129]
	v_pk_mul_f32 v[126:127], v[118:119], v[126:127]
	v_pk_mul_f32 v[114:115], v[106:107], v[114:115]
	v_pk_mul_f32 v[112:113], v[104:105], v[112:113]
	v_pk_mul_f32 v[110:111], v[102:103], v[110:111]
	v_pk_mul_f32 v[108:109], v[100:101], v[108:109]
	v_pk_mul_f32 v[98:99], v[90:91], v[98:99]
	v_pk_mul_f32 v[96:97], v[88:89], v[96:97]
	v_pk_mul_f32 v[94:95], v[86:87], v[94:95]
	v_pk_mul_f32 v[92:93], v[84:85], v[92:93]
	v_pk_mul_f32 v[82:83], v[74:75], v[82:83]
	v_pk_mul_f32 v[80:81], v[72:73], v[80:81]
	v_pk_mul_f32 v[78:79], v[70:71], v[78:79]
	v_pk_mul_f32 v[76:77], v[68:69], v[76:77]
	v_pk_mul_f32 v[66:67], v[58:59], v[66:67]
	v_pk_mul_f32 v[64:65], v[56:57], v[64:65]
	v_pk_mul_f32 v[62:63], v[54:55], v[62:63]
	v_pk_mul_f32 v[60:61], v[52:53], v[60:61]
	v_pk_mul_f32 v[50:51], v[42:43], v[50:51]
	v_pk_mul_f32 v[48:49], v[40:41], v[48:49]
	v_pk_mul_f32 v[46:47], v[38:39], v[46:47]
	v_pk_mul_f32 v[44:45], v[36:37], v[44:45]
	v_pk_mul_f32 v[34:35], v[26:27], v[34:35]
	v_pk_mul_f32 v[32:33], v[24:25], v[32:33]
	v_pk_mul_f32 v[30:31], v[22:23], v[30:31]
	v_pk_mul_f32 v[28:29], v[20:21], v[28:29]
	v_pk_mul_f32 v[18:19], v[10:11], v[18:19]
	v_pk_mul_f32 v[16:17], v[8:9], v[16:17]
	v_pk_mul_f32 v[14:15], v[6:7], v[14:15]
	v_pk_mul_f32 v[12:13], v[4:5], v[12:13]
	v_mad_i64_i32 v[152:153], s[2:3], v142, s16, v[144:145]
	s_nop 1
	v_mov_b32_e32 v143, v240
	v_lshlrev_b64 v[124:125], 1, v[154:155]
	v_lshl_add_u64 v[152:153], v[152:153], 0, v[124:125]
	s_nop 1
	s_nop 1
	s_nop 1
	v_mul_f32_e32 v154, 0xbfb8aa3b, v143
	v_pk_mul_f32 v[120:121], v[120:121], v[154:155] op_sel_hi:[1,0]
	v_pk_mul_f32 v[122:123], v[122:123], v[154:155] op_sel_hi:[1,0]
	v_pk_mul_f32 v[116:117], v[116:117], v[154:155] op_sel_hi:[1,0]
	v_pk_mul_f32 v[118:119], v[118:119], v[154:155] op_sel_hi:[1,0]
	v_exp_f32_e32 v120, v120
	v_exp_f32_e32 v121, v121
	v_exp_f32_e32 v122, v122
	v_exp_f32_e32 v123, v123
	v_exp_f32_e32 v116, v116
	v_exp_f32_e32 v117, v117
	v_exp_f32_e32 v118, v118
	v_exp_f32_e32 v119, v119
	v_pk_add_f32 v[120:121], v[120:121], 1.0 op_sel_hi:[1,0]
	v_pk_add_f32 v[122:123], v[122:123], 1.0 op_sel_hi:[1,0]
	v_pk_add_f32 v[116:117], v[116:117], 1.0 op_sel_hi:[1,0]
	v_pk_add_f32 v[118:119], v[118:119], 1.0 op_sel_hi:[1,0]
	v_rcp_f32_e32 v120, v120
	v_rcp_f32_e32 v121, v121
	v_rcp_f32_e32 v122, v122
	v_rcp_f32_e32 v123, v123
	v_rcp_f32_e32 v116, v116
	v_rcp_f32_e32 v117, v117
	v_rcp_f32_e32 v118, v118
	v_rcp_f32_e32 v119, v119
	v_mul_f32_e32 v156, v143, v143
	v_pk_mul_f32 v[120:121], v[156:157], v[120:121] op_sel_hi:[0,1]
	v_pk_mul_f32 v[122:123], v[156:157], v[122:123] op_sel_hi:[0,1]
	v_pk_mul_f32 v[116:117], v[156:157], v[116:117] op_sel_hi:[0,1]
	v_pk_mul_f32 v[118:119], v[156:157], v[118:119] op_sel_hi:[0,1]
	v_pk_mul_f32 v[120:121], v[128:129], v[120:121]
	v_pk_mul_f32 v[122:123], v[130:131], v[122:123]
	v_pk_mul_f32 v[128:129], v[158:159], v[116:117]
	v_pk_mul_f32 v[126:127], v[126:127], v[118:119]
	v_cvt_pk_bf16_f32 v116, v120, v121
	v_cvt_pk_bf16_f32 v117, v122, v123
	v_cvt_pk_bf16_f32 v118, v128, v129
	v_cvt_pk_bf16_f32 v119, v126, v127
	global_store_dwordx4 v[152:153], v[116:119], off
	s_nop 0
	s_nop 0
	v_mov_b32_e32 v119, v2
	v_mov_b32_e32 v119, v241
	s_nop 1
	v_add_u32_e32 v116, 16, v142
	v_mad_i64_i32 v[116:117], s[2:3], v116, s16, v[144:145]
	v_lshl_add_u64 v[116:117], v[116:117], 0, v[124:125]
	s_nop 0
	s_nop 1
	s_nop 1
	v_mul_f32_e32 v118, 0xbfb8aa3b, v119
	v_pk_mul_f32 v[104:105], v[104:105], v[118:119] op_sel_hi:[1,0]
	v_pk_mul_f32 v[106:107], v[106:107], v[118:119] op_sel_hi:[1,0]
	v_pk_mul_f32 v[100:101], v[100:101], v[118:119] op_sel_hi:[1,0]
	v_pk_mul_f32 v[102:103], v[102:103], v[118:119] op_sel_hi:[1,0]
	v_exp_f32_e32 v104, v104
	v_exp_f32_e32 v105, v105
	v_exp_f32_e32 v106, v106
	v_exp_f32_e32 v107, v107
	v_exp_f32_e32 v100, v100
	v_exp_f32_e32 v101, v101
	v_exp_f32_e32 v102, v102
	v_exp_f32_e32 v103, v103
	v_pk_add_f32 v[104:105], v[104:105], 1.0 op_sel_hi:[1,0]
	v_pk_add_f32 v[106:107], v[106:107], 1.0 op_sel_hi:[1,0]
	v_pk_add_f32 v[100:101], v[100:101], 1.0 op_sel_hi:[1,0]
	v_pk_add_f32 v[102:103], v[102:103], 1.0 op_sel_hi:[1,0]
	v_rcp_f32_e32 v104, v104
	v_rcp_f32_e32 v105, v105
	v_rcp_f32_e32 v106, v106
	v_rcp_f32_e32 v107, v107
	v_rcp_f32_e32 v100, v100
	v_rcp_f32_e32 v101, v101
	v_rcp_f32_e32 v102, v102
	v_rcp_f32_e32 v103, v103
	v_mul_f32_e32 v120, v119, v119
	v_pk_mul_f32 v[104:105], v[120:121], v[104:105] op_sel_hi:[0,1]
	v_pk_mul_f32 v[106:107], v[120:121], v[106:107] op_sel_hi:[0,1]
	v_pk_mul_f32 v[100:101], v[120:121], v[100:101] op_sel_hi:[0,1]
	v_pk_mul_f32 v[102:103], v[120:121], v[102:103] op_sel_hi:[0,1]
	v_pk_mul_f32 v[104:105], v[112:113], v[104:105]
	v_pk_mul_f32 v[106:107], v[114:115], v[106:107]
	v_pk_mul_f32 v[108:109], v[108:109], v[100:101]
	v_pk_mul_f32 v[110:111], v[110:111], v[102:103]
	v_cvt_pk_bf16_f32 v100, v104, v105
	v_cvt_pk_bf16_f32 v101, v106, v107
	v_cvt_pk_bf16_f32 v102, v108, v109
	v_cvt_pk_bf16_f32 v103, v110, v111
	global_store_dwordx4 v[116:117], v[100:103], off
	s_nop 0
	s_nop 0
	v_mov_b32_e32 v103, v2
	v_mov_b32_e32 v103, v242
	s_nop 1
	v_add_u32_e32 v100, 32, v142
; __device__ __forceinline__ float ss_get(const ss_t* p) { const ss_t v = *p; return (float)(unsigned)(v >> 32) + (float)(unsigned)v * 2.3283064365386963e-10f; }
; __device__ __forceinline__ unsigned pkbf(float lo, float hi) { typedef float f2_t __attribute__((ext_vector_type(2))); typedef __bf16 b2_t __attribute__((ext_vector_type(2))); f2_t v = {lo, hi}; b2_t b = __builtin_convertvector(v, b2_t); return __builtin_bit_cast(unsigned, b); }
; __device__ __forceinline__ f32x2 swiglu_pk(f32x2 g, f32x2 u, float c1, float rs2) {
;     const f32x2 z = g * c1; f32x2 e; e.x = __builtin_amdgcn_exp2f(z.x); e.y = __builtin_amdgcn_exp2f(z.y);
;     const f32x2 d = e + 1.0f; f32x2 r; r.x = __builtin_amdgcn_rcpf(d.x); r.y = __builtin_amdgcn_rcpf(d.y);
;     return (g * u) * (r * rs2);
; }
;     __device__ __forceinline__ void operator()(const f32x4 (&acc)[2][2][4][2], const Unit& u, int wr, int wc, int fr, int fq) const {
;     ...
;             for (int m = 0; m < 4; ++m) { const int row = row0 + ai * HALF + m * 16; bf16_t* rowp = O + (size_t)row * ldc + col0;
;                 const float rs = 1.0f / sqrtf(ss_get(ssq + row) * (1.0f / 2048.f) + 1e-6f);
;                 const float c1 = -1.4426950408889634f * rs, rs2 = rs * rs;
;                 const f32x4 ga = acc[ai][0][m][0], gb = acc[ai][0][m][1], ua = acc[ai][1][m][0], ub = acc[ai][1][m][1];
;                 u32x4 w;
;                 { const f32x2 o = swiglu_pk((f32x2){ga[0], ga[1]}, (f32x2){ua[0], ua[1]}, c1, rs2); w.x = pkbf(o.x, o.y); }
;                 { const f32x2 o = swiglu_pk((f32x2){ga[2], ga[3]}, (f32x2){ua[2], ua[3]}, c1, rs2); w.y = pkbf(o.x, o.y); }
;                 { const f32x2 o = swiglu_pk((f32x2){gb[0], gb[1]}, (f32x2){ub[0], ub[1]}, c1, rs2); w.z = pkbf(o.x, o.y); }
;                 { const f32x2 o = swiglu_pk((f32x2){gb[2], gb[3]}, (f32x2){ub[2], ub[3]}, c1, rs2); w.w = pkbf(o.x, o.y); }
;                 *(u32x4*)rowp = w; }
	v_mad_i64_i32 v[100:101], s[2:3], v100, s16, v[144:145]
	v_lshl_add_u64 v[100:101], v[100:101], 0, v[124:125]
	s_nop 0
	s_nop 1
	s_nop 1
	v_mul_f32_e32 v102, 0xbfb8aa3b, v103
	v_pk_mul_f32 v[88:89], v[88:89], v[102:103] op_sel_hi:[1,0]
	v_pk_mul_f32 v[90:91], v[90:91], v[102:103] op_sel_hi:[1,0]
	v_pk_mul_f32 v[84:85], v[84:85], v[102:103] op_sel_hi:[1,0]
	v_pk_mul_f32 v[86:87], v[86:87], v[102:103] op_sel_hi:[1,0]
	v_exp_f32_e32 v88, v88
	v_exp_f32_e32 v89, v89
	v_exp_f32_e32 v90, v90
	v_exp_f32_e32 v91, v91
	v_exp_f32_e32 v84, v84
	v_exp_f32_e32 v85, v85
	v_exp_f32_e32 v86, v86
	v_exp_f32_e32 v87, v87
	v_pk_add_f32 v[88:89], v[88:89], 1.0 op_sel_hi:[1,0]
	v_pk_add_f32 v[90:91], v[90:91], 1.0 op_sel_hi:[1,0]
	v_pk_add_f32 v[84:85], v[84:85], 1.0 op_sel_hi:[1,0]
	v_pk_add_f32 v[86:87], v[86:87], 1.0 op_sel_hi:[1,0]
	v_rcp_f32_e32 v88, v88
	v_rcp_f32_e32 v89, v89
	v_rcp_f32_e32 v90, v90
	v_rcp_f32_e32 v91, v91
	v_rcp_f32_e32 v84, v84
	v_rcp_f32_e32 v85, v85
	v_rcp_f32_e32 v86, v86
	v_rcp_f32_e32 v87, v87
	v_mul_f32_e32 v104, v103, v103
	v_pk_mul_f32 v[88:89], v[104:105], v[88:89] op_sel_hi:[0,1]
	v_pk_mul_f32 v[90:91], v[104:105], v[90:91] op_sel_hi:[0,1]
	v_pk_mul_f32 v[84:85], v[104:105], v[84:85] op_sel_hi:[0,1]
	v_pk_mul_f32 v[86:87], v[104:105], v[86:87] op_sel_hi:[0,1]
	v_pk_mul_f32 v[88:89], v[96:97], v[88:89]
	v_pk_mul_f32 v[90:91], v[98:99], v[90:91]
	v_pk_mul_f32 v[92:93], v[92:93], v[84:85]
	v_pk_mul_f32 v[94:95], v[94:95], v[86:87]
	v_cvt_pk_bf16_f32 v84, v88, v89
	v_cvt_pk_bf16_f32 v85, v90, v91
	v_cvt_pk_bf16_f32 v86, v92, v93
	v_cvt_pk_bf16_f32 v87, v94, v95
	global_store_dwordx4 v[100:101], v[84:87], off
	s_nop 0
	s_nop 0
	v_mov_b32_e32 v87, v2
	v_mov_b32_e32 v87, v243
	s_nop 1
	v_add_u32_e32 v84, 48, v142
	v_mad_i64_i32 v[84:85], s[2:3], v84, s16, v[144:145]
	v_lshl_add_u64 v[84:85], v[84:85], 0, v[124:125]
	s_nop 0
	s_nop 1
	s_nop 1
	v_mul_f32_e32 v86, 0xbfb8aa3b, v87
	v_pk_mul_f32 v[72:73], v[72:73], v[86:87] op_sel_hi:[1,0]
	v_pk_mul_f32 v[74:75], v[74:75], v[86:87] op_sel_hi:[1,0]
	v_pk_mul_f32 v[68:69], v[68:69], v[86:87] op_sel_hi:[1,0]
	v_pk_mul_f32 v[70:71], v[70:71], v[86:87] op_sel_hi:[1,0]
	v_exp_f32_e32 v72, v72
	v_exp_f32_e32 v73, v73
	v_exp_f32_e32 v74, v74
	v_exp_f32_e32 v75, v75
	v_exp_f32_e32 v68, v68
	v_exp_f32_e32 v69, v69
	v_exp_f32_e32 v70, v70
	v_exp_f32_e32 v71, v71
	v_pk_add_f32 v[72:73], v[72:73], 1.0 op_sel_hi:[1,0]
	v_pk_add_f32 v[74:75], v[74:75], 1.0 op_sel_hi:[1,0]
	v_pk_add_f32 v[68:69], v[68:69], 1.0 op_sel_hi:[1,0]
	v_pk_add_f32 v[70:71], v[70:71], 1.0 op_sel_hi:[1,0]
	v_rcp_f32_e32 v72, v72
	v_rcp_f32_e32 v73, v73
	v_rcp_f32_e32 v74, v74
	v_rcp_f32_e32 v75, v75
	v_rcp_f32_e32 v68, v68
	v_rcp_f32_e32 v69, v69
	v_rcp_f32_e32 v70, v70
	v_rcp_f32_e32 v71, v71
	v_mul_f32_e32 v88, v87, v87
	v_pk_mul_f32 v[72:73], v[88:89], v[72:73] op_sel_hi:[0,1]
	v_pk_mul_f32 v[74:75], v[88:89], v[74:75] op_sel_hi:[0,1]
	v_pk_mul_f32 v[68:69], v[88:89], v[68:69] op_sel_hi:[0,1]
	v_pk_mul_f32 v[70:71], v[88:89], v[70:71] op_sel_hi:[0,1]
	v_pk_mul_f32 v[72:73], v[80:81], v[72:73]
	v_pk_mul_f32 v[74:75], v[82:83], v[74:75]
	v_pk_mul_f32 v[76:77], v[76:77], v[68:69]
	v_pk_mul_f32 v[78:79], v[78:79], v[70:71]
	v_cvt_pk_bf16_f32 v68, v72, v73
	v_cvt_pk_bf16_f32 v69, v74, v75
	v_cvt_pk_bf16_f32 v70, v76, v77
	v_cvt_pk_bf16_f32 v71, v78, v79
	global_store_dwordx4 v[84:85], v[68:71], off
	s_nop 0
	s_nop 0
	v_mov_b32_e32 v71, v2
	v_mov_b32_e32 v71, v244
	s_nop 1
	v_add_u32_e32 v68, 0x80, v142
	v_mad_i64_i32 v[68:69], s[2:3], v68, s16, v[144:145]
	v_lshl_add_u64 v[68:69], v[68:69], 0, v[124:125]
	s_nop 0
	s_nop 1
	s_nop 1
	v_mul_f32_e32 v70, 0xbfb8aa3b, v71
	v_pk_mul_f32 v[56:57], v[56:57], v[70:71] op_sel_hi:[1,0]
	v_pk_mul_f32 v[58:59], v[58:59], v[70:71] op_sel_hi:[1,0]
	v_pk_mul_f32 v[52:53], v[52:53], v[70:71] op_sel_hi:[1,0]
	v_pk_mul_f32 v[54:55], v[54:55], v[70:71] op_sel_hi:[1,0]
	v_exp_f32_e32 v56, v56
	v_exp_f32_e32 v57, v57
	v_exp_f32_e32 v58, v58
	v_exp_f32_e32 v59, v59
	v_exp_f32_e32 v52, v52
	v_exp_f32_e32 v53, v53
	v_exp_f32_e32 v54, v54
	v_exp_f32_e32 v55, v55
	v_pk_add_f32 v[56:57], v[56:57], 1.0 op_sel_hi:[1,0]
	v_pk_add_f32 v[58:59], v[58:59], 1.0 op_sel_hi:[1,0]
	v_pk_add_f32 v[52:53], v[52:53], 1.0 op_sel_hi:[1,0]
	v_pk_add_f32 v[54:55], v[54:55], 1.0 op_sel_hi:[1,0]
	v_rcp_f32_e32 v56, v56
	v_rcp_f32_e32 v57, v57
	v_rcp_f32_e32 v58, v58
	v_rcp_f32_e32 v59, v59
	v_rcp_f32_e32 v52, v52
	v_rcp_f32_e32 v53, v53
	v_rcp_f32_e32 v54, v54
	v_rcp_f32_e32 v55, v55
	v_mul_f32_e32 v72, v71, v71
	v_pk_mul_f32 v[56:57], v[72:73], v[56:57] op_sel_hi:[0,1]
	v_pk_mul_f32 v[58:59], v[72:73], v[58:59] op_sel_hi:[0,1]
	v_pk_mul_f32 v[52:53], v[72:73], v[52:53] op_sel_hi:[0,1]
	v_pk_mul_f32 v[54:55], v[72:73], v[54:55] op_sel_hi:[0,1]
	v_pk_mul_f32 v[56:57], v[64:65], v[56:57]
	v_pk_mul_f32 v[58:59], v[66:67], v[58:59]
	v_pk_mul_f32 v[60:61], v[60:61], v[52:53]
	v_pk_mul_f32 v[62:63], v[62:63], v[54:55]
	v_cvt_pk_bf16_f32 v52, v56, v57
	v_cvt_pk_bf16_f32 v53, v58, v59
	v_cvt_pk_bf16_f32 v54, v60, v61
	v_cvt_pk_bf16_f32 v55, v62, v63
	global_store_dwordx4 v[68:69], v[52:55], off
	s_nop 0
	s_nop 0
	v_mov_b32_e32 v55, v2
	v_mov_b32_e32 v55, v245
	s_nop 1
; __device__ __forceinline__ float ss_get(const ss_t* p) { const ss_t v = *p; return (float)(unsigned)(v >> 32) + (float)(unsigned)v * 2.3283064365386963e-10f; }
; __device__ __forceinline__ unsigned pkbf(float lo, float hi) { typedef float f2_t __attribute__((ext_vector_type(2))); typedef __bf16 b2_t __attribute__((ext_vector_type(2))); f2_t v = {lo, hi}; b2_t b = __builtin_convertvector(v, b2_t); return __builtin_bit_cast(unsigned, b); }
; __device__ __forceinline__ f32x2 swiglu_pk(f32x2 g, f32x2 u, float c1, float rs2) {
;     const f32x2 z = g * c1; f32x2 e; e.x = __builtin_amdgcn_exp2f(z.x); e.y = __builtin_amdgcn_exp2f(z.y);
;     const f32x2 d = e + 1.0f; f32x2 r; r.x = __builtin_amdgcn_rcpf(d.x); r.y = __builtin_amdgcn_rcpf(d.y);
;     return (g * u) * (r * rs2);
; }
;     __device__ __forceinline__ void operator()(const f32x4 (&acc)[2][2][4][2], const Unit& u, int wr, int wc, int fr, int fq) const {
;     ...
;             for (int m = 0; m < 4; ++m) { const int row = row0 + ai * HALF + m * 16; bf16_t* rowp = O + (size_t)row * ldc + col0;
;                 const float rs = 1.0f / sqrtf(ss_get(ssq + row) * (1.0f / 2048.f) + 1e-6f);
;                 const float c1 = -1.4426950408889634f * rs, rs2 = rs * rs;
;                 const f32x4 ga = acc[ai][0][m][0], gb = acc[ai][0][m][1], ua = acc[ai][1][m][0], ub = acc[ai][1][m][1];
;                 u32x4 w;
;                 { const f32x2 o = swiglu_pk((f32x2){ga[0], ga[1]}, (f32x2){ua[0], ua[1]}, c1, rs2); w.x = pkbf(o.x, o.y); }
;                 { const f32x2 o = swiglu_pk((f32x2){ga[2], ga[3]}, (f32x2){ua[2], ua[3]}, c1, rs2); w.y = pkbf(o.x, o.y); }
;                 { const f32x2 o = swiglu_pk((f32x2){gb[0], gb[1]}, (f32x2){ub[0], ub[1]}, c1, rs2); w.z = pkbf(o.x, o.y); }
;                 { const f32x2 o = swiglu_pk((f32x2){gb[2], gb[3]}, (f32x2){ub[2], ub[3]}, c1, rs2); w.w = pkbf(o.x, o.y); }
;                 *(u32x4*)rowp = w; }
	v_add_u32_e32 v52, 0x90, v142
	v_mad_i64_i32 v[52:53], s[2:3], v52, s16, v[144:145]
	v_lshl_add_u64 v[52:53], v[52:53], 0, v[124:125]
	s_nop 0
	s_nop 1
	s_nop 1
	v_mul_f32_e32 v54, 0xbfb8aa3b, v55
	v_pk_mul_f32 v[40:41], v[40:41], v[54:55] op_sel_hi:[1,0]
	v_pk_mul_f32 v[42:43], v[42:43], v[54:55] op_sel_hi:[1,0]
	v_pk_mul_f32 v[36:37], v[36:37], v[54:55] op_sel_hi:[1,0]
	v_pk_mul_f32 v[38:39], v[38:39], v[54:55] op_sel_hi:[1,0]
	v_exp_f32_e32 v40, v40
	v_exp_f32_e32 v41, v41
	v_exp_f32_e32 v42, v42
	v_exp_f32_e32 v43, v43
	v_exp_f32_e32 v36, v36
	v_exp_f32_e32 v37, v37
	v_exp_f32_e32 v38, v38
	v_exp_f32_e32 v39, v39
	v_pk_add_f32 v[40:41], v[40:41], 1.0 op_sel_hi:[1,0]
	v_pk_add_f32 v[42:43], v[42:43], 1.0 op_sel_hi:[1,0]
	v_pk_add_f32 v[36:37], v[36:37], 1.0 op_sel_hi:[1,0]
	v_pk_add_f32 v[38:39], v[38:39], 1.0 op_sel_hi:[1,0]
	v_rcp_f32_e32 v40, v40
	v_rcp_f32_e32 v41, v41
	v_rcp_f32_e32 v42, v42
	v_rcp_f32_e32 v43, v43
	v_rcp_f32_e32 v36, v36
	v_rcp_f32_e32 v37, v37
	v_rcp_f32_e32 v38, v38
	v_rcp_f32_e32 v39, v39
	v_mul_f32_e32 v56, v55, v55
	v_pk_mul_f32 v[40:41], v[56:57], v[40:41] op_sel_hi:[0,1]
	v_pk_mul_f32 v[42:43], v[56:57], v[42:43] op_sel_hi:[0,1]
	v_pk_mul_f32 v[36:37], v[56:57], v[36:37] op_sel_hi:[0,1]
	v_pk_mul_f32 v[38:39], v[56:57], v[38:39] op_sel_hi:[0,1]
	v_pk_mul_f32 v[40:41], v[48:49], v[40:41]
	v_pk_mul_f32 v[42:43], v[50:51], v[42:43]
	v_pk_mul_f32 v[44:45], v[44:45], v[36:37]
	v_pk_mul_f32 v[46:47], v[46:47], v[38:39]
	v_cvt_pk_bf16_f32 v36, v40, v41
	v_cvt_pk_bf16_f32 v37, v42, v43
	v_cvt_pk_bf16_f32 v38, v44, v45
	v_cvt_pk_bf16_f32 v39, v46, v47
	global_store_dwordx4 v[52:53], v[36:39], off
	s_nop 0
	s_nop 0
	v_mov_b32_e32 v39, v2
	v_mov_b32_e32 v39, v246
	s_nop 1
	v_add_u32_e32 v36, 0xa0, v142
	v_mad_i64_i32 v[36:37], s[2:3], v36, s16, v[144:145]
	v_lshl_add_u64 v[36:37], v[36:37], 0, v[124:125]
	s_nop 0
	s_nop 1
	s_nop 1
	v_mul_f32_e32 v38, 0xbfb8aa3b, v39
	v_pk_mul_f32 v[24:25], v[24:25], v[38:39] op_sel_hi:[1,0]
	v_pk_mul_f32 v[26:27], v[26:27], v[38:39] op_sel_hi:[1,0]
	v_pk_mul_f32 v[20:21], v[20:21], v[38:39] op_sel_hi:[1,0]
	v_pk_mul_f32 v[22:23], v[22:23], v[38:39] op_sel_hi:[1,0]
	v_exp_f32_e32 v24, v24
	v_exp_f32_e32 v25, v25
	v_exp_f32_e32 v26, v26
	v_exp_f32_e32 v27, v27
	v_exp_f32_e32 v20, v20
	v_exp_f32_e32 v21, v21
	v_exp_f32_e32 v22, v22
	v_exp_f32_e32 v23, v23
	v_pk_add_f32 v[24:25], v[24:25], 1.0 op_sel_hi:[1,0]
	v_pk_add_f32 v[26:27], v[26:27], 1.0 op_sel_hi:[1,0]
	v_pk_add_f32 v[20:21], v[20:21], 1.0 op_sel_hi:[1,0]
	v_pk_add_f32 v[22:23], v[22:23], 1.0 op_sel_hi:[1,0]
	v_rcp_f32_e32 v24, v24
	v_rcp_f32_e32 v25, v25
	v_rcp_f32_e32 v26, v26
	v_rcp_f32_e32 v27, v27
	v_rcp_f32_e32 v20, v20
	v_rcp_f32_e32 v21, v21
	v_rcp_f32_e32 v22, v22
	v_rcp_f32_e32 v23, v23
	v_mul_f32_e32 v40, v39, v39
	v_pk_mul_f32 v[24:25], v[40:41], v[24:25] op_sel_hi:[0,1]
	v_pk_mul_f32 v[26:27], v[40:41], v[26:27] op_sel_hi:[0,1]
	v_pk_mul_f32 v[20:21], v[40:41], v[20:21] op_sel_hi:[0,1]
	v_pk_mul_f32 v[22:23], v[40:41], v[22:23] op_sel_hi:[0,1]
	v_pk_mul_f32 v[24:25], v[32:33], v[24:25]
	v_pk_mul_f32 v[26:27], v[34:35], v[26:27]
	v_pk_mul_f32 v[28:29], v[28:29], v[20:21]
	v_pk_mul_f32 v[30:31], v[30:31], v[22:23]
	v_cvt_pk_bf16_f32 v20, v24, v25
	v_cvt_pk_bf16_f32 v21, v26, v27
	v_cvt_pk_bf16_f32 v22, v28, v29
	v_cvt_pk_bf16_f32 v23, v30, v31
	global_store_dwordx4 v[36:37], v[20:23], off
	s_nop 0
	s_nop 0
	v_mov_b32_e32 v23, v2
	v_mov_b32_e32 v23, v252
	s_nop 1
	v_add_u32_e32 v20, 0xb0, v142
	v_mad_i64_i32 v[20:21], s[2:3], v20, s16, v[144:145]
	v_lshl_add_u64 v[20:21], v[20:21], 0, v[124:125]
	s_nop 0
	s_nop 1
	s_nop 1
	s_mov_b64 s[2:3], -1
	v_mul_f32_e32 v22, 0xbfb8aa3b, v23
	v_pk_mul_f32 v[8:9], v[8:9], v[22:23] op_sel_hi:[1,0]
	v_pk_mul_f32 v[10:11], v[10:11], v[22:23] op_sel_hi:[1,0]
	v_pk_mul_f32 v[4:5], v[4:5], v[22:23] op_sel_hi:[1,0]
	v_pk_mul_f32 v[6:7], v[6:7], v[22:23] op_sel_hi:[1,0]
	v_exp_f32_e32 v8, v8
	v_exp_f32_e32 v9, v9
	v_exp_f32_e32 v10, v10
	v_exp_f32_e32 v11, v11
	v_exp_f32_e32 v4, v4
	v_exp_f32_e32 v5, v5
	v_exp_f32_e32 v6, v6
	v_exp_f32_e32 v7, v7
	v_pk_add_f32 v[8:9], v[8:9], 1.0 op_sel_hi:[1,0]
	v_pk_add_f32 v[10:11], v[10:11], 1.0 op_sel_hi:[1,0]
	v_pk_add_f32 v[4:5], v[4:5], 1.0 op_sel_hi:[1,0]
	v_pk_add_f32 v[6:7], v[6:7], 1.0 op_sel_hi:[1,0]
	v_rcp_f32_e32 v8, v8
	v_rcp_f32_e32 v9, v9
	v_rcp_f32_e32 v10, v10
	v_rcp_f32_e32 v11, v11
	v_rcp_f32_e32 v4, v4
	v_rcp_f32_e32 v5, v5
	v_rcp_f32_e32 v6, v6
	v_rcp_f32_e32 v7, v7
	v_mul_f32_e32 v24, v23, v23
	v_pk_mul_f32 v[8:9], v[24:25], v[8:9] op_sel_hi:[0,1]
	v_pk_mul_f32 v[10:11], v[24:25], v[10:11] op_sel_hi:[0,1]
	v_pk_mul_f32 v[4:5], v[24:25], v[4:5] op_sel_hi:[0,1]
	v_pk_mul_f32 v[6:7], v[24:25], v[6:7] op_sel_hi:[0,1]
	v_pk_mul_f32 v[8:9], v[16:17], v[8:9]
	v_pk_mul_f32 v[10:11], v[18:19], v[10:11]
	v_pk_mul_f32 v[12:13], v[12:13], v[4:5]
	v_pk_mul_f32 v[14:15], v[14:15], v[6:7]
	s_andn2_b64 vcc, exec, s[14:15]
	v_cvt_pk_bf16_f32 v4, v8, v9
	v_cvt_pk_bf16_f32 v5, v10, v11
	v_cvt_pk_bf16_f32 v6, v12, v13
	v_cvt_pk_bf16_f32 v7, v14, v15
	global_store_dwordx4 v[20:21], v[4:7], off
	s_cbranch_vccnz .LBB0_1049
	s_andn2_b64 vcc, exec, s[8:9]
	s_cbranch_vccnz .LBB0_1048
	s_barrier
	s_branch .LBB0_1048

; __global__ void __launch_bounds__(NWAVES * 64, 2) fwd_kernel(Args A) {
;     extern __shared__ __attribute__((aligned(16))) unsigned char lds[];
	.amdhsa_kernel _Z10fwd_kernel4Args
		.amdhsa_group_segment_fixed_size 0
		.amdhsa_private_segment_fixed_size 0
		.amdhsa_kernarg_size 416
		.amdhsa_user_sgpr_count 2
		.amdhsa_user_sgpr_dispatch_ptr 0
		.amdhsa_user_sgpr_queue_ptr 0
		.amdhsa_user_sgpr_kernarg_segment_ptr 1
		.amdhsa_user_sgpr_dispatch_id 0
		.amdhsa_user_sgpr_kernarg_preload_length 0
		.amdhsa_user_sgpr_kernarg_preload_offset 0
		.amdhsa_user_sgpr_private_segment_size 0
		.amdhsa_uses_dynamic_stack 0
		.amdhsa_enable_private_segment 0
		.amdhsa_system_sgpr_workgroup_id_x 1
		.amdhsa_system_sgpr_workgroup_id_y 0
		.amdhsa_system_sgpr_workgroup_id_z 0
		.amdhsa_system_sgpr_workgroup_info 0
		.amdhsa_system_vgpr_workitem_id 2
		.amdhsa_next_free_vgpr 254
		.amdhsa_next_free_sgpr 102
		.amdhsa_accum_offset 256
		.amdhsa_reserve_vcc 1
		.amdhsa_float_round_mode_32 0
		.amdhsa_float_round_mode_16_64 0
		.amdhsa_float_denorm_mode_32 3
		.amdhsa_float_denorm_mode_16_64 3
		.amdhsa_dx10_clamp 1
		.amdhsa_ieee_mode 1
		.amdhsa_fp16_overflow 0
		.amdhsa_tg_split 0
		.amdhsa_exception_fp_ieee_invalid_op 0
		.amdhsa_exception_fp_denorm_src 0
		.amdhsa_exception_fp_ieee_div_zero 0
		.amdhsa_exception_fp_ieee_overflow 0
		.amdhsa_exception_fp_ieee_underflow 0
		.amdhsa_exception_fp_ieee_inexact 0
		.amdhsa_exception_int_div_zero 0
	.end_amdhsa_kernel

; __global__ void __launch_bounds__(NWAVES * 64, 2) fwd_kernel(Args A) {
;     extern __shared__ __attribute__((aligned(16))) unsigned char lds[];
amdhsa.kernels:
  - .agpr_count:     0
    .args:
      - .offset:         0
        .size:           160
        .value_kind:     by_value
      - .offset:         160
        .size:           4
        .value_kind:     hidden_block_count_x
      - .offset:         164
        .size:           4
        .value_kind:     hidden_block_count_y
      - .offset:         168
        .size:           4
        .value_kind:     hidden_block_count_z
      - .offset:         172
        .size:           2
        .value_kind:     hidden_group_size_x
      - .offset:         174
        .size:           2
        .value_kind:     hidden_group_size_y
      - .offset:         176
        .size:           2
        .value_kind:     hidden_group_size_z
      - .offset:         178
        .size:           2
        .value_kind:     hidden_remainder_x
      - .offset:         180
        .size:           2
        .value_kind:     hidden_remainder_y
      - .offset:         182
        .size:           2
        .value_kind:     hidden_remainder_z
      - .offset:         200
        .size:           8
        .value_kind:     hidden_global_offset_x
      - .offset:         208
        .size:           8
        .value_kind:     hidden_global_offset_y
      - .offset:         216
        .size:           8
        .value_kind:     hidden_global_offset_z
      - .offset:         224
        .size:           2
        .value_kind:     hidden_grid_dims
      - .offset:         248
        .size:           8
        .value_kind:     hidden_multigrid_sync_arg
      - .offset:         280
        .size:           4
        .value_kind:     hidden_dynamic_lds_size
    .group_segment_fixed_size: 0
    .kernarg_segment_align: 8
    .kernarg_segment_size: 416
    .language:       OpenCL C
    .language_version:
      - 2
      - 0
    .max_flat_workgroup_size: 512
    .name:           _Z10fwd_kernel4Args
    .private_segment_fixed_size: 0
    .sgpr_count:     108
    .sgpr_spill_count: 274
    .symbol:         _Z10fwd_kernel4Args.kd
    .uniform_work_group_size: 1
    .uses_dynamic_stack: false
    .vgpr_count:     254
    .vgpr_spill_count: 0
    .wavefront_size: 64
